# merge adjacent scalar f32 mul/add pairs of the SwiGLU and sigmoid GEMM epilogues into packed ops (201 pairs)
# baseline (speedup 1.0000x reference)
;     __device__ __forceinline__ void operator()(const AccT& acc, const Unit& u, int wr, int wc, int fr, int fq) const {
;         const int row0 = u.pm * 256 + wr * 64 + fr, col0 = u.pn * 128 + wc * 32 + 8 * fq;
;         float rsv[2][4];
;         { f32x4 pv[2][4];
; #pragma unroll
;           for (int ai = 0; ai < 2; ++ai)
; #pragma unroll
;               for (int m = 0; m < 4; ++m) pv[ai][m] = *(const f32x4*)(ss + (size_t)(row0 + ai * 128 + m * 16) * 16 + fq * 4);
; #pragma unroll
;           for (int ai = 0; ai < 2; ++ai)
; #pragma unroll
;               for (int m = 0; m < 4; ++m) { const f32x4 a = pv[ai][m]; float t = (a[0] + a[1]) + (a[2] + a[3]); t = xsum_16_32(t); rsv[ai][m] = rsqrtf(t * (1.0f / DM) + EPS); } }
.LBB0_181:
	v_mov_b32_e32 v210, 1.0
	v_lshl_add_u32 v180, s89, 8, v184
	v_ashrrev_i32_e32 v181, 31, v180
	v_lshlrev_b64 v[130:131], 6, v[180:181]
	v_or_b32_e32 v178, 16, v180
	v_lshl_add_u64 v[130:131], v[160:161], 0, v[130:131]
	v_ashrrev_i32_e32 v179, 31, v178
	global_load_dwordx4 v[188:191], v[130:131], off
	v_lshlrev_b64 v[130:131], 6, v[178:179]
	v_lshl_add_u64 v[130:131], v[160:161], 0, v[130:131]
	global_load_dwordx4 v[206:209], v[130:131], off
	v_or_b32_e32 v176, 32, v180
	v_ashrrev_i32_e32 v177, 31, v176
	v_lshlrev_b64 v[130:131], 6, v[176:177]
	v_or_b32_e32 v174, 48, v180
	v_lshl_add_u64 v[130:131], v[160:161], 0, v[130:131]
	v_ashrrev_i32_e32 v175, 31, v174
	global_load_dwordx4 v[150:153], v[130:131], off
	v_lshlrev_b64 v[130:131], 6, v[174:175]
	v_lshl_add_u64 v[130:131], v[160:161], 0, v[130:131]
	global_load_dwordx4 v[146:149], v[130:131], off
	v_add_u32_e32 v172, 0x80, v180
	v_ashrrev_i32_e32 v173, 31, v172
	v_lshlrev_b64 v[130:131], 6, v[172:173]
	v_add_u32_e32 v170, 0x90, v180
	v_lshl_add_u64 v[130:131], v[160:161], 0, v[130:131]
	v_ashrrev_i32_e32 v171, 31, v170
	global_load_dwordx4 v[142:145], v[130:131], off
	v_lshlrev_b64 v[130:131], 6, v[170:171]
	v_lshl_add_u64 v[130:131], v[160:161], 0, v[130:131]
	global_load_dwordx4 v[138:141], v[130:131], off
	v_add_u32_e32 v168, 0xa0, v180
	v_ashrrev_i32_e32 v169, 31, v168
	v_lshlrev_b64 v[130:131], 6, v[168:169]
	v_add_u32_e32 v166, 0xb0, v180
	v_lshl_add_u64 v[130:131], v[160:161], 0, v[130:131]
	v_ashrrev_i32_e32 v167, 31, v166
	global_load_dwordx4 v[134:137], v[130:131], off
	v_lshlrev_b64 v[130:131], 6, v[166:167]
	v_lshl_add_u64 v[130:131], v[160:161], 0, v[130:131]
	global_load_dwordx4 v[130:133], v[130:131], off
	s_mov_b32 s0, 0x358637bd
	v_pk_mul_f32 v[120:121], v[120:121], v[116:117]
	v_pk_mul_f32 v[128:129], v[128:129], v[124:125]
	v_pk_mul_f32 v[112:113], v[112:113], v[108:109]
	v_pk_mul_f32 v[104:105], v[104:105], v[100:101]
	v_pk_mul_f32 v[96:97], v[96:97], v[92:93]
	v_pk_mul_f32 v[88:89], v[88:89], v[84:85]
	v_pk_mul_f32 v[80:81], v[80:81], v[76:77]
	v_pk_mul_f32 v[72:73], v[72:73], v[68:69]
	v_pk_mul_f32 v[64:65], v[64:65], v[60:61]
	v_pk_mul_f32 v[56:57], v[56:57], v[52:53]
	v_pk_mul_f32 v[48:49], v[48:49], v[44:45]
	v_pk_mul_f32 v[40:41], v[40:41], v[36:37]
	v_pk_mul_f32 v[32:33], v[32:33], v[28:29]
	v_pk_mul_f32 v[24:25], v[24:25], v[20:21]
	v_pk_mul_f32 v[16:17], v[16:17], v[12:13]
	v_pk_mul_f32 v[8:9], v[8:9], v[4:5]
	s_waitcnt vmcnt(0)
	v_mov_b32_e32 v182, v189
	v_mov_b32_e32 v183, v190
	v_mov_b32_e32 v189, v191
	v_pk_add_f32 v[182:183], v[182:183], v[188:189]
	v_mov_b32_e32 v190, v207
	v_pk_add_f32 v[182:183], v[182:183], v[182:183] op_sel:[0,1] op_sel_hi:[1,0]
	v_mov_b32_e32 v191, v208
	v_mov_b32_e32 v207, v209
	v_mov_b32_e32 v167, v182
	v_pk_add_f32 v[190:191], v[190:191], v[206:207]
	s_nop 0
	v_permlane16_swap_b32_e32 v182, v167
	v_pk_add_f32 v[190:191], v[190:191], v[190:191] op_sel:[0,1] op_sel_hi:[1,0]
	v_add_f32_e32 v183, v182, v167
	v_mov_b32_e32 v167, v190
	s_nop 1
	v_permlane16_swap_b32_e32 v190, v167
	v_add_f32_e32 v182, v190, v167
	v_mov_b32_e32 v189, v183
	v_mov_b32_e32 v188, v182
	s_nop 0
	v_permlane32_swap_b32_e32 v183, v189
	v_permlane32_swap_b32_e32 v182, v188
	v_pk_add_f32 v[188:189], v[182:183], v[188:189]
	v_mov_b64_e32 v[182:183], s[0:1]
	v_pk_fma_f32 v[188:189], v[188:189], s[4:5], v[182:183] op_sel_hi:[1,0,0]
	s_nop 0
	v_mul_f32_e32 v167, 0x4b800000, v189
	v_cmp_gt_f32_e64 s[40:41], s50, v189
	v_cmp_gt_f32_e32 vcc, s50, v188
	s_nop 0
	v_cndmask_b32_e64 v167, v189, v167, s[40:41]
	v_rsq_f32_e32 v167, v167
	v_mov_b32_e32 v189, v152
	v_mul_f32_e32 v169, 0x45800000, v167
	v_cndmask_b32_e64 v169, v167, v169, s[40:41]
	v_mul_f32_e32 v167, 0x4b800000, v188
	v_cndmask_b32_e32 v167, v188, v167, vcc
	v_mov_b32_e32 v188, v151
	v_mov_b32_e32 v151, v153
	v_pk_add_f32 v[150:151], v[188:189], v[150:151]
	v_mov_b32_e32 v188, v147
	v_mov_b32_e32 v189, v148
	v_mov_b32_e32 v147, v149
	v_pk_add_f32 v[146:147], v[188:189], v[146:147]
	v_pk_add_f32 v[150:151], v[150:151], v[150:151] op_sel:[0,1] op_sel_hi:[1,0]
	v_pk_add_f32 v[146:147], v[146:147], v[146:147] op_sel:[0,1] op_sel_hi:[1,0]
	v_mov_b32_e32 v151, v150
	v_mov_b32_e32 v147, v146
	s_nop 0
	v_permlane16_swap_b32_e32 v150, v151
	v_permlane16_swap_b32_e32 v146, v147
	v_add_f32_e32 v151, v150, v151
	v_add_f32_e32 v150, v146, v147
	v_mov_b32_e32 v153, v151
	v_mov_b32_e32 v152, v150
	s_nop 0
	v_permlane32_swap_b32_e32 v151, v153
	v_permlane32_swap_b32_e32 v150, v152
	v_pk_add_f32 v[146:147], v[150:151], v[152:153]
	v_rsq_f32_e32 v167, v167
	v_pk_fma_f32 v[146:147], v[146:147], s[4:5], v[182:183] op_sel_hi:[1,0,0]
	v_mov_b32_e32 v149, v144
	v_mul_f32_e32 v148, 0x4b800000, v147
	v_cmp_gt_f32_e64 s[40:41], s50, v147
	v_mul_f32_e32 v171, 0x45800000, v167
	v_cndmask_b32_e32 v167, v167, v171, vcc
	v_cndmask_b32_e64 v147, v147, v148, s[40:41]
	v_rsq_f32_e32 v147, v147
	v_cmp_gt_f32_e32 vcc, s50, v146
	v_mul_f32_e32 v148, 0x45800000, v147
	v_cndmask_b32_e64 v147, v147, v148, s[40:41]
	v_mul_f32_e32 v148, 0x4b800000, v146
	v_cndmask_b32_e32 v146, v146, v148, vcc
	v_rsq_f32_e32 v146, v146
	s_nop 0
	v_mul_f32_e32 v148, 0x45800000, v146
	v_cndmask_b32_e32 v146, v146, v148, vcc
	v_mov_b32_e32 v148, v143
	v_mov_b32_e32 v143, v145
	v_pk_add_f32 v[142:143], v[148:149], v[142:143]
	v_mov_b32_e32 v148, v139
	v_mov_b32_e32 v149, v140
	v_mov_b32_e32 v139, v141
	v_pk_add_f32 v[138:139], v[148:149], v[138:139]
	v_pk_add_f32 v[142:143], v[142:143], v[142:143] op_sel:[0,1] op_sel_hi:[1,0]
	v_pk_add_f32 v[138:139], v[138:139], v[138:139] op_sel:[0,1] op_sel_hi:[1,0]
	v_mov_b32_e32 v143, v142
	v_mov_b32_e32 v139, v138
; __device__ __forceinline__ unsigned cvtpk(float lo, float hi) { f32x2_t v = {lo, hi}; bf16x2_t b = __builtin_convertvector(v, bf16x2_t); return __builtin_bit_cast(unsigned, b); }
;     __device__ __forceinline__ void operator()(const AccT& acc, const Unit& u, int wr, int wc, int fr, int fq) const {
;     ...
;             for (int m = 0; m < 4; ++m) { const int row = row0 + ai * 128 + m * 16; const float rs = rsv[ai][m]; const float c1 = -rs * LOG2E, c2 = rs * rs;
;                 float a[8];
; #pragma unroll
;                 for (int n = 0; n < 2; ++n)
; #pragma unroll
;                     for (int j = 0; j < 4; ++j) { const float g_ = acc[ai][0][m][n][j]; a[n * 4 + j] = (g_ * acc[ai][1][m][n][j]) * (c2 * __builtin_amdgcn_rcpf(1.0f + __builtin_amdgcn_exp2f(g_ * c1))); }
;                 u32x4 w; w.x = cvtpk(a[0], a[1]); w.y = cvtpk(a[2], a[3]); w.z = cvtpk(a[4], a[5]); w.w = cvtpk(a[6], a[7]);
;                 *(u32x4*)(O + (size_t)row * DFF + col0) = w; }
	s_nop 0
	v_permlane16_swap_b32_e32 v142, v143
	v_permlane16_swap_b32_e32 v138, v139
	v_add_f32_e32 v143, v142, v143
	v_add_f32_e32 v142, v138, v139
	v_mov_b32_e32 v145, v143
	v_mov_b32_e32 v144, v142
	s_nop 0
	v_permlane32_swap_b32_e32 v143, v145
	v_permlane32_swap_b32_e32 v142, v144
	v_pk_add_f32 v[138:139], v[142:143], v[144:145]
	v_mov_b32_e32 v141, v136
	v_pk_fma_f32 v[138:139], v[138:139], s[4:5], v[182:183] op_sel_hi:[1,0,0]
	s_nop 0
	v_mul_f32_e32 v140, 0x4b800000, v139
	v_cmp_gt_f32_e64 s[40:41], s50, v139
	v_cmp_gt_f32_e32 vcc, s50, v138
	s_nop 0
	v_cndmask_b32_e64 v139, v139, v140, s[40:41]
	v_rsq_f32_e32 v139, v139
	s_nop 0
	v_mul_f32_e32 v140, 0x45800000, v139
	v_cndmask_b32_e64 v139, v139, v140, s[40:41]
	v_mul_f32_e32 v140, 0x4b800000, v138
	v_cndmask_b32_e32 v138, v138, v140, vcc
	v_rsq_f32_e32 v138, v138
	s_nop 0
	v_mul_f32_e32 v140, 0x45800000, v138
	v_cndmask_b32_e32 v138, v138, v140, vcc
	v_mov_b32_e32 v140, v135
	v_mov_b32_e32 v135, v137
	v_pk_add_f32 v[134:135], v[140:141], v[134:135]
	v_mov_b32_e32 v140, v131
	v_mov_b32_e32 v141, v132
	v_mov_b32_e32 v131, v133
	v_pk_add_f32 v[130:131], v[140:141], v[130:131]
	v_pk_add_f32 v[134:135], v[134:135], v[134:135] op_sel:[0,1] op_sel_hi:[1,0]
	v_pk_add_f32 v[130:131], v[130:131], v[130:131] op_sel:[0,1] op_sel_hi:[1,0]
	v_mov_b32_e32 v135, v134
	v_mov_b32_e32 v131, v130
	s_nop 0
	v_permlane16_swap_b32_e32 v134, v135
	v_permlane16_swap_b32_e32 v130, v131
	v_add_f32_e32 v135, v134, v135
	v_add_f32_e32 v134, v130, v131
	v_mov_b32_e32 v137, v135
	v_mov_b32_e32 v136, v134
	s_nop 0
	v_permlane32_swap_b32_e32 v135, v137
	v_permlane32_swap_b32_e32 v134, v136
	v_pk_add_f32 v[130:131], v[134:135], v[136:137]
	v_mul_f32_e32 v135, 0xbfb8aa3b, v169
	v_pk_mul_f32 v[136:137], v[122:123], v[134:135] op_sel:[0,1]
	s_nop 0
	v_exp_f32_e32 v136, v136
	v_exp_f32_e32 v137, v137
	v_pk_fma_f32 v[130:131], v[130:131], s[4:5], v[182:183] op_sel_hi:[1,0,0]
	v_mul_f32_e32 v134, v169, v169
	v_pk_add_f32 v[136:137], v[210:211], v[136:137] op_sel_hi:[0,1]
	s_nop 0
	v_rcp_f32_e32 v136, v136
	v_rcp_f32_e32 v137, v137
	v_mul_f32_e32 v132, 0x4b800000, v131
	v_cmp_gt_f32_e64 s[40:41], s50, v131
	v_pk_mul_f32 v[122:123], v[126:127], v[122:123]
	v_pk_mul_f32 v[126:127], v[134:135], v[136:137] op_sel_hi:[0,1]
	v_cndmask_b32_e64 v131, v131, v132, s[40:41]
	v_rsq_f32_e32 v131, v131
	v_pk_mul_f32 v[122:123], v[122:123], v[126:127]
	v_pk_mul_f32 v[126:127], v[114:115], v[134:135] op_sel:[0,1]
	s_nop 0
	v_exp_f32_e32 v126, v126
	v_exp_f32_e32 v127, v127
	v_pk_mul_f32 v[116:117], v[116:117], v[134:135] op_sel:[0,1]
	v_pk_mul_f32 v[124:125], v[124:125], v[134:135] op_sel:[0,1]
	v_exp_f32_e32 v116, v116
	v_exp_f32_e32 v117, v117
	v_mul_f32_e32 v132, 0x45800000, v131
	v_exp_f32_e32 v124, v124
	v_exp_f32_e32 v125, v125
	v_cmp_gt_f32_e32 vcc, s50, v130
	v_cndmask_b32_e64 v131, v131, v132, s[40:41]
	v_mul_f32_e32 v132, 0x4b800000, v130
	v_cndmask_b32_e32 v130, v130, v132, vcc
	v_pk_add_f32 v[126:127], v[210:211], v[126:127] op_sel_hi:[0,1]
	v_rsq_f32_e32 v130, v130
	v_rcp_f32_e32 v126, v126
	v_rcp_f32_e32 v127, v127
	v_pk_add_f32 v[116:117], v[210:211], v[116:117] op_sel_hi:[0,1]
	v_pk_add_f32 v[124:125], v[210:211], v[124:125] op_sel_hi:[0,1]
	v_rcp_f32_e32 v116, v116
	v_rcp_f32_e32 v117, v117
	v_rcp_f32_e32 v124, v124
	v_rcp_f32_e32 v125, v125
	v_mul_f32_e32 v132, 0x45800000, v130
	v_pk_mul_f32 v[114:115], v[118:119], v[114:115]
	v_pk_mul_f32 v[118:119], v[134:135], v[126:127] op_sel_hi:[0,1]
	v_cndmask_b32_e32 v130, v130, v132, vcc
	v_lshl_or_b32 v132, s14, 7, v186
	v_pk_mul_f32 v[114:115], v[114:115], v[118:119]
	v_pk_mul_f32 v[116:117], v[134:135], v[116:117] op_sel_hi:[0,1]
	v_ashrrev_i32_e32 v133, 31, v132
	v_pk_mul_f32 v[124:125], v[134:135], v[124:125] op_sel_hi:[0,1]
	v_pk_mul_f32 v[116:117], v[120:121], v[116:117]
	v_cvt_pk_bf16_f32 v120, v114, v115
	v_mov_b64_e32 v[114:115], s[70:71]
	v_pk_mul_f32 v[124:125], v[128:129], v[124:125]
	v_cvt_pk_bf16_f32 v118, v122, v123
	v_cvt_pk_bf16_f32 v121, v116, v117
	v_mad_i64_i32 v[122:123], s[0:1], v180, s97, v[114:115]
	v_lshlrev_b64 v[116:117], 1, v[132:133]
	v_cvt_pk_bf16_f32 v119, v124, v125
	v_lshl_add_u64 v[122:123], v[122:123], 0, v[116:117]
	global_store_dwordx4 v[122:123], v[118:121], off
	s_and_b64 vcc, exec, s[38:39]
	s_nop 0
	v_mul_f32_e32 v119, 0xbfb8aa3b, v167
	v_pk_mul_f32 v[120:121], v[106:107], v[118:119] op_sel:[0,1]
	s_nop 0
	v_exp_f32_e32 v120, v120
	v_exp_f32_e32 v121, v121
	v_mul_f32_e32 v118, v167, v167
	v_pk_mul_f32 v[106:107], v[110:111], v[106:107]
	v_pk_add_f32 v[120:121], v[210:211], v[120:121] op_sel_hi:[0,1]
	s_nop 0
	v_rcp_f32_e32 v120, v120
	v_rcp_f32_e32 v121, v121
	v_pk_mul_f32 v[108:109], v[108:109], v[118:119] op_sel:[0,1]
	s_nop 0
	v_exp_f32_e32 v108, v108
	v_pk_mul_f32 v[110:111], v[118:119], v[120:121] op_sel_hi:[0,1]
	v_pk_mul_f32 v[106:107], v[106:107], v[110:111]
	v_pk_mul_f32 v[110:111], v[98:99], v[118:119] op_sel:[0,1]
	s_nop 0
	v_exp_f32_e32 v110, v110
	v_exp_f32_e32 v111, v111
	v_pk_mul_f32 v[98:99], v[102:103], v[98:99]
	v_exp_f32_e32 v109, v109
	v_pk_add_f32 v[110:111], v[210:211], v[110:111] op_sel_hi:[0,1]
	s_nop 0
	v_rcp_f32_e32 v110, v110
	v_rcp_f32_e32 v111, v111
	v_pk_add_f32 v[108:109], v[210:211], v[108:109] op_sel_hi:[0,1]
	s_nop 0
	v_rcp_f32_e32 v108, v108
	v_pk_mul_f32 v[102:103], v[118:119], v[110:111] op_sel_hi:[0,1]
	v_pk_mul_f32 v[102:103], v[98:99], v[102:103]
	v_pk_mul_f32 v[98:99], v[100:101], v[118:119] op_sel:[0,1]
	s_nop 0
	v_exp_f32_e32 v98, v98
	v_exp_f32_e32 v99, v99
	v_rcp_f32_e32 v109, v109
	v_cvt_pk_bf16_f32 v100, v102, v103
	v_pk_add_f32 v[98:99], v[210:211], v[98:99] op_sel_hi:[0,1]
	s_nop 0
; __device__ __forceinline__ unsigned cvtpk(float lo, float hi) { f32x2_t v = {lo, hi}; bf16x2_t b = __builtin_convertvector(v, bf16x2_t); return __builtin_bit_cast(unsigned, b); }
;     __device__ __forceinline__ void operator()(const AccT& acc, const Unit& u, int wr, int wc, int fr, int fq) const {
;     ...
;             for (int m = 0; m < 4; ++m) { const int row = row0 + ai * 128 + m * 16; const float rs = rsv[ai][m]; const float c1 = -rs * LOG2E, c2 = rs * rs;
;                 float a[8];
; #pragma unroll
;                 for (int n = 0; n < 2; ++n)
; #pragma unroll
;                     for (int j = 0; j < 4; ++j) { const float g_ = acc[ai][0][m][n][j]; a[n * 4 + j] = (g_ * acc[ai][1][m][n][j]) * (c2 * __builtin_amdgcn_rcpf(1.0f + __builtin_amdgcn_exp2f(g_ * c1))); }
;                 u32x4 w; w.x = cvtpk(a[0], a[1]); w.y = cvtpk(a[2], a[3]); w.z = cvtpk(a[4], a[5]); w.w = cvtpk(a[6], a[7]);
;                 *(u32x4*)(O + (size_t)row * DFF + col0) = w; }
	v_rcp_f32_e32 v98, v98
	v_rcp_f32_e32 v99, v99
	v_pk_mul_f32 v[108:109], v[118:119], v[108:109] op_sel_hi:[0,1]
	v_pk_mul_f32 v[108:109], v[112:113], v[108:109]
	v_mad_i64_i32 v[102:103], s[0:1], v178, s97, v[114:115]
	v_pk_mul_f32 v[98:99], v[118:119], v[98:99] op_sel_hi:[0,1]
	v_pk_mul_f32 v[104:105], v[104:105], v[98:99]
	v_cvt_pk_bf16_f32 v98, v106, v107
	v_cvt_pk_bf16_f32 v99, v108, v109
	v_cvt_pk_bf16_f32 v101, v104, v105
	v_lshl_add_u64 v[102:103], v[102:103], 0, v[116:117]
	global_store_dwordx4 v[102:103], v[98:101], off
	s_nop 1
	v_mul_f32_e32 v99, 0xbfb8aa3b, v147
	v_pk_mul_f32 v[100:101], v[90:91], v[98:99] op_sel:[0,1]
	s_nop 0
	v_exp_f32_e32 v100, v100
	v_exp_f32_e32 v101, v101
	v_mul_f32_e32 v98, v147, v147
	v_pk_mul_f32 v[90:91], v[94:95], v[90:91]
	v_pk_add_f32 v[100:101], v[210:211], v[100:101] op_sel_hi:[0,1]
	s_nop 0
	v_rcp_f32_e32 v100, v100
	v_rcp_f32_e32 v101, v101
	v_pk_mul_f32 v[92:93], v[92:93], v[98:99] op_sel:[0,1]
	s_nop 0
	v_exp_f32_e32 v92, v92
	v_pk_mul_f32 v[94:95], v[98:99], v[100:101] op_sel_hi:[0,1]
	v_pk_mul_f32 v[90:91], v[90:91], v[94:95]
	v_pk_mul_f32 v[94:95], v[82:83], v[98:99] op_sel:[0,1]
	s_nop 0
	v_exp_f32_e32 v94, v94
	v_exp_f32_e32 v95, v95
	v_pk_mul_f32 v[82:83], v[86:87], v[82:83]
	v_exp_f32_e32 v93, v93
	v_pk_add_f32 v[94:95], v[210:211], v[94:95] op_sel_hi:[0,1]
	s_nop 0
	v_rcp_f32_e32 v94, v94
	v_rcp_f32_e32 v95, v95
	v_pk_add_f32 v[92:93], v[210:211], v[92:93] op_sel_hi:[0,1]
	s_nop 0
	v_rcp_f32_e32 v92, v92
	v_pk_mul_f32 v[86:87], v[98:99], v[94:95] op_sel_hi:[0,1]
	v_pk_mul_f32 v[86:87], v[82:83], v[86:87]
	v_pk_mul_f32 v[82:83], v[84:85], v[98:99] op_sel:[0,1]
	s_nop 0
	v_exp_f32_e32 v82, v82
	v_exp_f32_e32 v83, v83
	v_rcp_f32_e32 v93, v93
	v_cvt_pk_bf16_f32 v84, v86, v87
	v_pk_add_f32 v[82:83], v[210:211], v[82:83] op_sel_hi:[0,1]
	s_nop 0
	v_rcp_f32_e32 v82, v82
	v_rcp_f32_e32 v83, v83
	v_pk_mul_f32 v[92:93], v[98:99], v[92:93] op_sel_hi:[0,1]
	v_pk_mul_f32 v[92:93], v[96:97], v[92:93]
	v_mad_i64_i32 v[86:87], s[0:1], v176, s97, v[114:115]
	v_pk_mul_f32 v[82:83], v[98:99], v[82:83] op_sel_hi:[0,1]
	v_pk_mul_f32 v[88:89], v[88:89], v[82:83]
	v_cvt_pk_bf16_f32 v82, v90, v91
	v_cvt_pk_bf16_f32 v83, v92, v93
	v_cvt_pk_bf16_f32 v85, v88, v89
	v_lshl_add_u64 v[86:87], v[86:87], 0, v[116:117]
	global_store_dwordx4 v[86:87], v[82:85], off
	s_nop 1
	v_mul_f32_e32 v83, 0xbfb8aa3b, v146
	v_pk_mul_f32 v[84:85], v[74:75], v[82:83] op_sel:[0,1]
	s_nop 0
	v_exp_f32_e32 v84, v84
	v_exp_f32_e32 v85, v85
	v_mul_f32_e32 v82, v146, v146
	v_pk_mul_f32 v[74:75], v[78:79], v[74:75]
	v_pk_add_f32 v[84:85], v[210:211], v[84:85] op_sel_hi:[0,1]
	s_nop 0
	v_rcp_f32_e32 v84, v84
	v_rcp_f32_e32 v85, v85
	v_pk_mul_f32 v[76:77], v[76:77], v[82:83] op_sel:[0,1]
	s_nop 0
	v_exp_f32_e32 v76, v76
	v_pk_mul_f32 v[78:79], v[82:83], v[84:85] op_sel_hi:[0,1]
	v_pk_mul_f32 v[74:75], v[74:75], v[78:79]
	v_pk_mul_f32 v[78:79], v[66:67], v[82:83] op_sel:[0,1]
	s_nop 0
	v_exp_f32_e32 v78, v78
	v_exp_f32_e32 v79, v79
	v_pk_mul_f32 v[66:67], v[70:71], v[66:67]
	v_exp_f32_e32 v77, v77
	v_pk_add_f32 v[78:79], v[210:211], v[78:79] op_sel_hi:[0,1]
	s_nop 0
	v_rcp_f32_e32 v78, v78
	v_rcp_f32_e32 v79, v79
	v_pk_add_f32 v[76:77], v[210:211], v[76:77] op_sel_hi:[0,1]
	s_nop 0
	v_rcp_f32_e32 v76, v76
	v_pk_mul_f32 v[70:71], v[82:83], v[78:79] op_sel_hi:[0,1]
	v_pk_mul_f32 v[70:71], v[66:67], v[70:71]
	v_pk_mul_f32 v[66:67], v[68:69], v[82:83] op_sel:[0,1]
	s_nop 0
	v_exp_f32_e32 v66, v66
	v_exp_f32_e32 v67, v67
	v_rcp_f32_e32 v77, v77
	v_cvt_pk_bf16_f32 v68, v70, v71
	v_pk_add_f32 v[66:67], v[210:211], v[66:67] op_sel_hi:[0,1]
	s_nop 0
	v_rcp_f32_e32 v66, v66
	v_rcp_f32_e32 v67, v67
	v_pk_mul_f32 v[76:77], v[82:83], v[76:77] op_sel_hi:[0,1]
	v_pk_mul_f32 v[76:77], v[80:81], v[76:77]
	v_mad_i64_i32 v[70:71], s[0:1], v174, s97, v[114:115]
	v_pk_mul_f32 v[66:67], v[82:83], v[66:67] op_sel_hi:[0,1]
	v_pk_mul_f32 v[72:73], v[72:73], v[66:67]
	v_cvt_pk_bf16_f32 v66, v74, v75
	v_cvt_pk_bf16_f32 v67, v76, v77
	v_cvt_pk_bf16_f32 v69, v72, v73
	v_lshl_add_u64 v[70:71], v[70:71], 0, v[116:117]
	global_store_dwordx4 v[70:71], v[66:69], off
	s_nop 1
	v_mul_f32_e32 v67, 0xbfb8aa3b, v139
	v_pk_mul_f32 v[68:69], v[58:59], v[66:67] op_sel:[0,1]
	s_nop 0
	v_exp_f32_e32 v68, v68
	v_exp_f32_e32 v69, v69
	v_mul_f32_e32 v66, v139, v139
	v_pk_mul_f32 v[58:59], v[62:63], v[58:59]
	v_pk_add_f32 v[68:69], v[210:211], v[68:69] op_sel_hi:[0,1]
	s_nop 0
	v_rcp_f32_e32 v68, v68
	v_rcp_f32_e32 v69, v69
	v_pk_mul_f32 v[60:61], v[60:61], v[66:67] op_sel:[0,1]
	s_nop 0
	v_exp_f32_e32 v60, v60
	v_pk_mul_f32 v[62:63], v[66:67], v[68:69] op_sel_hi:[0,1]
	v_pk_mul_f32 v[58:59], v[58:59], v[62:63]
	v_pk_mul_f32 v[62:63], v[50:51], v[66:67] op_sel:[0,1]
	s_nop 0
	v_exp_f32_e32 v62, v62
	v_exp_f32_e32 v63, v63
	v_pk_mul_f32 v[50:51], v[54:55], v[50:51]
	v_exp_f32_e32 v61, v61
	v_pk_add_f32 v[62:63], v[210:211], v[62:63] op_sel_hi:[0,1]
	s_nop 0
	v_rcp_f32_e32 v62, v62
	v_rcp_f32_e32 v63, v63
	v_pk_add_f32 v[60:61], v[210:211], v[60:61] op_sel_hi:[0,1]
	s_nop 0
	v_rcp_f32_e32 v60, v60
	v_pk_mul_f32 v[54:55], v[66:67], v[62:63] op_sel_hi:[0,1]
	v_pk_mul_f32 v[54:55], v[50:51], v[54:55]
	v_pk_mul_f32 v[50:51], v[52:53], v[66:67] op_sel:[0,1]
	s_nop 0
	v_exp_f32_e32 v50, v50
	v_exp_f32_e32 v51, v51
	v_rcp_f32_e32 v61, v61
	v_cvt_pk_bf16_f32 v52, v54, v55
	v_pk_add_f32 v[50:51], v[210:211], v[50:51] op_sel_hi:[0,1]
	s_nop 0
	v_rcp_f32_e32 v50, v50
	v_rcp_f32_e32 v51, v51
	v_pk_mul_f32 v[60:61], v[66:67], v[60:61] op_sel_hi:[0,1]
	v_pk_mul_f32 v[60:61], v[64:65], v[60:61]
	v_mad_i64_i32 v[54:55], s[0:1], v172, s97, v[114:115]
	v_pk_mul_f32 v[50:51], v[66:67], v[50:51] op_sel_hi:[0,1]
; __device__ __forceinline__ unsigned cvtpk(float lo, float hi) { f32x2_t v = {lo, hi}; bf16x2_t b = __builtin_convertvector(v, bf16x2_t); return __builtin_bit_cast(unsigned, b); }
; #define PG8_BAR __builtin_amdgcn_s_barrier()
; template <class Epi, class Sched>
; __device__ __forceinline__ void gemm_phase(LAS unsigned char* lds, const Gemm g, const Sched& S, const Epi& E) {
;     ...
;         if (!has_next) break;
; #pragma unroll
;         for (int a = 0; a < 2; ++a)
; #pragma unroll
;             for (int b = 0; b < 2; ++b)
; #pragma unroll
;                 for (int m = 0; m < 4; ++m)
; #pragma unroll
;                     for (int n = 0; n < 2; ++n) acc[a][b][m][n] = (f32x4){0.f, 0.f, 0.f, 0.f};
;         cur = nxt; cA = nA; cB = nB; ++ui;
;         if (wr == 1) PG8_BAR;
;     }
;     __device__ __forceinline__ void operator()(const AccT& acc, const Unit& u, int wr, int wc, int fr, int fq) const {
;     ...
;             for (int m = 0; m < 4; ++m) { const int row = row0 + ai * 128 + m * 16; const float rs = rsv[ai][m]; const float c1 = -rs * LOG2E, c2 = rs * rs;
;                 float a[8];
; #pragma unroll
;                 for (int n = 0; n < 2; ++n)
; #pragma unroll
;                     for (int j = 0; j < 4; ++j) { const float g_ = acc[ai][0][m][n][j]; a[n * 4 + j] = (g_ * acc[ai][1][m][n][j]) * (c2 * __builtin_amdgcn_rcpf(1.0f + __builtin_amdgcn_exp2f(g_ * c1))); }
;                 u32x4 w; w.x = cvtpk(a[0], a[1]); w.y = cvtpk(a[2], a[3]); w.z = cvtpk(a[4], a[5]); w.w = cvtpk(a[6], a[7]);
;                 *(u32x4*)(O + (size_t)row * DFF + col0) = w; }
	v_pk_mul_f32 v[56:57], v[56:57], v[50:51]
	v_cvt_pk_bf16_f32 v50, v58, v59
	v_cvt_pk_bf16_f32 v51, v60, v61
	v_cvt_pk_bf16_f32 v53, v56, v57
	v_lshl_add_u64 v[54:55], v[54:55], 0, v[116:117]
	global_store_dwordx4 v[54:55], v[50:53], off
	s_nop 1
	v_mul_f32_e32 v51, 0xbfb8aa3b, v138
	v_pk_mul_f32 v[52:53], v[42:43], v[50:51] op_sel:[0,1]
	s_nop 0
	v_exp_f32_e32 v52, v52
	v_exp_f32_e32 v53, v53
	v_mul_f32_e32 v50, v138, v138
	v_pk_mul_f32 v[42:43], v[46:47], v[42:43]
	v_pk_add_f32 v[52:53], v[210:211], v[52:53] op_sel_hi:[0,1]
	s_nop 0
	v_rcp_f32_e32 v52, v52
	v_rcp_f32_e32 v53, v53
	v_pk_mul_f32 v[44:45], v[44:45], v[50:51] op_sel:[0,1]
	s_nop 0
	v_exp_f32_e32 v44, v44
	v_pk_mul_f32 v[46:47], v[50:51], v[52:53] op_sel_hi:[0,1]
	v_pk_mul_f32 v[42:43], v[42:43], v[46:47]
	v_pk_mul_f32 v[46:47], v[34:35], v[50:51] op_sel:[0,1]
	s_nop 0
	v_exp_f32_e32 v46, v46
	v_exp_f32_e32 v47, v47
	v_pk_mul_f32 v[34:35], v[38:39], v[34:35]
	v_exp_f32_e32 v45, v45
	v_pk_add_f32 v[46:47], v[210:211], v[46:47] op_sel_hi:[0,1]
	s_nop 0
	v_rcp_f32_e32 v46, v46
	v_rcp_f32_e32 v47, v47
	v_pk_add_f32 v[44:45], v[210:211], v[44:45] op_sel_hi:[0,1]
	s_nop 0
	v_rcp_f32_e32 v44, v44
	v_pk_mul_f32 v[38:39], v[50:51], v[46:47] op_sel_hi:[0,1]
	v_pk_mul_f32 v[38:39], v[34:35], v[38:39]
	v_pk_mul_f32 v[34:35], v[36:37], v[50:51] op_sel:[0,1]
	s_nop 0
	v_exp_f32_e32 v34, v34
	v_exp_f32_e32 v35, v35
	v_rcp_f32_e32 v45, v45
	v_cvt_pk_bf16_f32 v36, v38, v39
	v_pk_add_f32 v[34:35], v[210:211], v[34:35] op_sel_hi:[0,1]
	s_nop 0
	v_rcp_f32_e32 v34, v34
	v_rcp_f32_e32 v35, v35
	v_pk_mul_f32 v[44:45], v[50:51], v[44:45] op_sel_hi:[0,1]
	v_pk_mul_f32 v[44:45], v[48:49], v[44:45]
	v_mad_i64_i32 v[38:39], s[0:1], v170, s97, v[114:115]
	v_pk_mul_f32 v[34:35], v[50:51], v[34:35] op_sel_hi:[0,1]
	v_pk_mul_f32 v[40:41], v[40:41], v[34:35]
	v_cvt_pk_bf16_f32 v34, v42, v43
	v_cvt_pk_bf16_f32 v35, v44, v45
	v_cvt_pk_bf16_f32 v37, v40, v41
	v_lshl_add_u64 v[38:39], v[38:39], 0, v[116:117]
	global_store_dwordx4 v[38:39], v[34:37], off
	s_nop 1
	v_mul_f32_e32 v35, 0xbfb8aa3b, v131
	v_pk_mul_f32 v[36:37], v[26:27], v[34:35] op_sel:[0,1]
	s_nop 0
	v_exp_f32_e32 v36, v36
	v_exp_f32_e32 v37, v37
	v_mul_f32_e32 v34, v131, v131
	v_pk_mul_f32 v[26:27], v[30:31], v[26:27]
	v_pk_add_f32 v[36:37], v[210:211], v[36:37] op_sel_hi:[0,1]
	s_nop 0
	v_rcp_f32_e32 v36, v36
	v_rcp_f32_e32 v37, v37
	v_pk_mul_f32 v[28:29], v[28:29], v[34:35] op_sel:[0,1]
	s_nop 0
	v_exp_f32_e32 v28, v28
	v_pk_mul_f32 v[30:31], v[34:35], v[36:37] op_sel_hi:[0,1]
	v_pk_mul_f32 v[26:27], v[26:27], v[30:31]
	v_pk_mul_f32 v[30:31], v[18:19], v[34:35] op_sel:[0,1]
	s_nop 0
	v_exp_f32_e32 v30, v30
	v_exp_f32_e32 v31, v31
	v_pk_mul_f32 v[18:19], v[22:23], v[18:19]
	v_exp_f32_e32 v29, v29
	v_pk_add_f32 v[30:31], v[210:211], v[30:31] op_sel_hi:[0,1]
	s_nop 0
	v_rcp_f32_e32 v30, v30
	v_rcp_f32_e32 v31, v31
	v_pk_add_f32 v[28:29], v[210:211], v[28:29] op_sel_hi:[0,1]
	s_nop 0
	v_rcp_f32_e32 v28, v28
	v_pk_mul_f32 v[22:23], v[34:35], v[30:31] op_sel_hi:[0,1]
	v_pk_mul_f32 v[22:23], v[18:19], v[22:23]
	v_pk_mul_f32 v[18:19], v[20:21], v[34:35] op_sel:[0,1]
	s_nop 0
	v_exp_f32_e32 v18, v18
	v_exp_f32_e32 v19, v19
	v_rcp_f32_e32 v29, v29
	v_cvt_pk_bf16_f32 v20, v22, v23
	v_pk_add_f32 v[18:19], v[210:211], v[18:19] op_sel_hi:[0,1]
	s_nop 0
	v_rcp_f32_e32 v18, v18
	v_rcp_f32_e32 v19, v19
	v_pk_mul_f32 v[28:29], v[34:35], v[28:29] op_sel_hi:[0,1]
	v_pk_mul_f32 v[28:29], v[32:33], v[28:29]
	v_mad_i64_i32 v[22:23], s[0:1], v168, s97, v[114:115]
	v_pk_mul_f32 v[18:19], v[34:35], v[18:19] op_sel_hi:[0,1]
	v_pk_mul_f32 v[24:25], v[24:25], v[18:19]
	v_cvt_pk_bf16_f32 v18, v26, v27
	v_cvt_pk_bf16_f32 v19, v28, v29
	v_cvt_pk_bf16_f32 v21, v24, v25
	v_lshl_add_u64 v[22:23], v[22:23], 0, v[116:117]
	global_store_dwordx4 v[22:23], v[18:21], off
	s_nop 1
	v_mul_f32_e32 v19, 0xbfb8aa3b, v130
	v_pk_mul_f32 v[20:21], v[10:11], v[18:19] op_sel:[0,1]
	s_nop 0
	v_exp_f32_e32 v20, v20
	v_exp_f32_e32 v21, v21
	v_mul_f32_e32 v18, v130, v130
	v_pk_mul_f32 v[10:11], v[14:15], v[10:11]
	v_pk_add_f32 v[20:21], v[210:211], v[20:21] op_sel_hi:[0,1]
	s_nop 0
	v_rcp_f32_e32 v20, v20
	v_rcp_f32_e32 v21, v21
	v_pk_mul_f32 v[12:13], v[12:13], v[18:19] op_sel:[0,1]
	s_nop 0
	v_exp_f32_e32 v12, v12
	v_pk_mul_f32 v[14:15], v[18:19], v[20:21] op_sel_hi:[0,1]
	v_pk_mul_f32 v[10:11], v[10:11], v[14:15]
	v_pk_mul_f32 v[14:15], v[2:3], v[18:19] op_sel:[0,1]
	s_nop 0
	v_exp_f32_e32 v14, v14
	v_exp_f32_e32 v15, v15
	v_pk_mul_f32 v[2:3], v[6:7], v[2:3]
	v_exp_f32_e32 v13, v13
	v_pk_add_f32 v[14:15], v[210:211], v[14:15] op_sel_hi:[0,1]
	s_nop 0
	v_rcp_f32_e32 v14, v14
	v_rcp_f32_e32 v15, v15
	v_pk_add_f32 v[12:13], v[210:211], v[12:13] op_sel_hi:[0,1]
	s_nop 0
	v_rcp_f32_e32 v12, v12
	v_pk_mul_f32 v[6:7], v[18:19], v[14:15] op_sel_hi:[0,1]
	v_pk_mul_f32 v[6:7], v[2:3], v[6:7]
	v_pk_mul_f32 v[2:3], v[4:5], v[18:19] op_sel:[0,1]
	s_nop 0
	v_exp_f32_e32 v2, v2
	v_exp_f32_e32 v3, v3
	v_rcp_f32_e32 v13, v13
	v_cvt_pk_bf16_f32 v4, v6, v7
	v_pk_add_f32 v[2:3], v[210:211], v[2:3] op_sel_hi:[0,1]
	s_nop 0
	v_rcp_f32_e32 v2, v2
	v_rcp_f32_e32 v3, v3
	v_pk_mul_f32 v[12:13], v[18:19], v[12:13] op_sel_hi:[0,1]
	v_pk_mul_f32 v[12:13], v[16:17], v[12:13]
	v_mad_i64_i32 v[6:7], s[0:1], v166, s97, v[114:115]
	v_pk_mul_f32 v[2:3], v[18:19], v[2:3] op_sel_hi:[0,1]
	v_pk_mul_f32 v[8:9], v[8:9], v[2:3]
	v_cvt_pk_bf16_f32 v2, v10, v11
	v_cvt_pk_bf16_f32 v3, v12, v13
	v_cvt_pk_bf16_f32 v5, v8, v9
	v_lshl_add_u64 v[6:7], v[6:7], 0, v[116:117]
	s_mov_b64 s[0:1], -1
	global_store_dwordx4 v[6:7], v[2:5], off
	s_cbranch_vccnz .LBB0_169
	s_andn2_b64 vcc, exec, s[54:55]
	s_cbranch_vccnz .LBB0_168
	s_barrier
	s_branch .LBB0_168

;     __device__ __forceinline__ void operator()(const AccT& acc, const Unit& u, int wr, int wc, int fr, int fq) const {
;         const int row0 = u.pm * 256 + wr * 64 + fr, col0 = u.pn * 256 + wc * 32 + 8 * fq;
;         float rsv[2][4];
;         { f32x4 pv[2][4];
; #pragma unroll
;           for (int ai = 0; ai < 2; ++ai)
; #pragma unroll
;               for (int m = 0; m < 4; ++m) pv[ai][m] = *(const f32x4*)(ss + (size_t)(row0 + ai * 128 + m * 16) * 16 + fq * 4);
; #pragma unroll
;           for (int ai = 0; ai < 2; ++ai)
; #pragma unroll
;               for (int m = 0; m < 4; ++m) { const f32x4 a = pv[ai][m]; float t = (a[0] + a[1]) + (a[2] + a[3]); t = xsum_16_32(t); rsv[ai][m] = rsqrtf(t * (1.0f / DM) + EPS); } }
.LBB0_1443:
	v_mov_b32_e32 v210, 1.0
	v_lshl_add_u32 v180, s90, 8, v184
	v_ashrrev_i32_e32 v181, 31, v180
	v_lshlrev_b64 v[130:131], 6, v[180:181]
	v_or_b32_e32 v178, 16, v180
	v_lshl_add_u64 v[130:131], v[160:161], 0, v[130:131]
	v_ashrrev_i32_e32 v179, 31, v178
	global_load_dwordx4 v[188:191], v[130:131], off
	v_lshlrev_b64 v[130:131], 6, v[178:179]
	v_lshl_add_u64 v[130:131], v[160:161], 0, v[130:131]
	global_load_dwordx4 v[206:209], v[130:131], off
	v_or_b32_e32 v176, 32, v180
	v_ashrrev_i32_e32 v177, 31, v176
	v_lshlrev_b64 v[130:131], 6, v[176:177]
	v_or_b32_e32 v174, 48, v180
	v_lshl_add_u64 v[130:131], v[160:161], 0, v[130:131]
	v_ashrrev_i32_e32 v175, 31, v174
	global_load_dwordx4 v[150:153], v[130:131], off
	v_lshlrev_b64 v[130:131], 6, v[174:175]
	v_lshl_add_u64 v[130:131], v[160:161], 0, v[130:131]
	global_load_dwordx4 v[146:149], v[130:131], off
	v_add_u32_e32 v172, 0x80, v180
	v_ashrrev_i32_e32 v173, 31, v172
	v_lshlrev_b64 v[130:131], 6, v[172:173]
	v_add_u32_e32 v170, 0x90, v180
	v_lshl_add_u64 v[130:131], v[160:161], 0, v[130:131]
	v_ashrrev_i32_e32 v171, 31, v170
	global_load_dwordx4 v[142:145], v[130:131], off
	v_lshlrev_b64 v[130:131], 6, v[170:171]
	v_lshl_add_u64 v[130:131], v[160:161], 0, v[130:131]
	global_load_dwordx4 v[138:141], v[130:131], off
	v_add_u32_e32 v168, 0xa0, v180
	v_ashrrev_i32_e32 v169, 31, v168
	v_lshlrev_b64 v[130:131], 6, v[168:169]
	v_add_u32_e32 v166, 0xb0, v180
	v_lshl_add_u64 v[130:131], v[160:161], 0, v[130:131]
	v_ashrrev_i32_e32 v167, 31, v166
	global_load_dwordx4 v[134:137], v[130:131], off
	v_lshlrev_b64 v[130:131], 6, v[166:167]
	v_lshl_add_u64 v[130:131], v[160:161], 0, v[130:131]
	global_load_dwordx4 v[130:133], v[130:131], off
	s_mov_b32 s0, 0x358637bd
	s_waitcnt vmcnt(0)
	v_mov_b32_e32 v182, v189
	v_mov_b32_e32 v183, v190
	v_mov_b32_e32 v189, v191
	v_pk_add_f32 v[182:183], v[182:183], v[188:189]
	v_mov_b32_e32 v190, v207
	v_pk_add_f32 v[182:183], v[182:183], v[182:183] op_sel:[0,1] op_sel_hi:[1,0]
	v_mov_b32_e32 v191, v208
	v_mov_b32_e32 v207, v209
	v_mov_b32_e32 v167, v182
	v_pk_add_f32 v[190:191], v[190:191], v[206:207]
	s_nop 0
	v_permlane16_swap_b32_e32 v182, v167
	v_pk_add_f32 v[190:191], v[190:191], v[190:191] op_sel:[0,1] op_sel_hi:[1,0]
	v_add_f32_e32 v183, v182, v167
	v_mov_b32_e32 v167, v190
	s_nop 1
	v_permlane16_swap_b32_e32 v190, v167
	v_add_f32_e32 v182, v190, v167
	v_mov_b32_e32 v189, v183
	v_mov_b32_e32 v188, v182
	s_nop 0
	v_permlane32_swap_b32_e32 v183, v189
	v_permlane32_swap_b32_e32 v182, v188
	v_pk_add_f32 v[188:189], v[182:183], v[188:189]
	v_mov_b64_e32 v[182:183], s[0:1]
	v_pk_fma_f32 v[188:189], v[188:189], s[4:5], v[182:183] op_sel_hi:[1,0,0]
	s_nop 0
	v_mul_f32_e32 v167, 0x4b800000, v189
	v_cmp_gt_f32_e64 s[46:47], s50, v189
	v_cmp_gt_f32_e32 vcc, s50, v188
	s_nop 0
	v_cndmask_b32_e64 v167, v189, v167, s[46:47]
	v_rsq_f32_e32 v167, v167
	v_mov_b32_e32 v189, v152
	v_mul_f32_e32 v169, 0x45800000, v167
	v_cndmask_b32_e64 v169, v167, v169, s[46:47]
	v_mul_f32_e32 v167, 0x4b800000, v188
	v_cndmask_b32_e32 v167, v188, v167, vcc
	v_mov_b32_e32 v188, v151
	v_mov_b32_e32 v151, v153
	v_pk_add_f32 v[150:151], v[188:189], v[150:151]
	v_mov_b32_e32 v188, v147
	v_mov_b32_e32 v189, v148
	v_mov_b32_e32 v147, v149
	v_pk_add_f32 v[146:147], v[188:189], v[146:147]
	v_pk_add_f32 v[150:151], v[150:151], v[150:151] op_sel:[0,1] op_sel_hi:[1,0]
	v_pk_add_f32 v[146:147], v[146:147], v[146:147] op_sel:[0,1] op_sel_hi:[1,0]
	v_mov_b32_e32 v151, v150
	v_mov_b32_e32 v147, v146
	s_nop 0
	v_permlane16_swap_b32_e32 v150, v151
	v_permlane16_swap_b32_e32 v146, v147
	v_add_f32_e32 v151, v150, v151
	v_add_f32_e32 v150, v146, v147
	v_mov_b32_e32 v153, v151
	v_mov_b32_e32 v152, v150
	s_nop 0
	v_permlane32_swap_b32_e32 v151, v153
	v_permlane32_swap_b32_e32 v150, v152
	v_pk_add_f32 v[146:147], v[150:151], v[152:153]
	v_rsq_f32_e32 v167, v167
	v_pk_fma_f32 v[146:147], v[146:147], s[4:5], v[182:183] op_sel_hi:[1,0,0]
	v_mov_b32_e32 v149, v144
	v_mul_f32_e32 v148, 0x4b800000, v147
	v_cmp_gt_f32_e64 s[46:47], s50, v147
	v_mul_f32_e32 v171, 0x45800000, v167
	v_cndmask_b32_e32 v167, v167, v171, vcc
	v_cndmask_b32_e64 v147, v147, v148, s[46:47]
	v_rsq_f32_e32 v147, v147
	v_cmp_gt_f32_e32 vcc, s50, v146
	v_mul_f32_e32 v148, 0x45800000, v147
	v_cndmask_b32_e64 v147, v147, v148, s[46:47]
	v_mul_f32_e32 v148, 0x4b800000, v146
	v_cndmask_b32_e32 v146, v146, v148, vcc
	v_rsq_f32_e32 v146, v146
	s_nop 0
	v_mul_f32_e32 v148, 0x45800000, v146
	v_cndmask_b32_e32 v146, v146, v148, vcc
	v_mov_b32_e32 v148, v143
	v_mov_b32_e32 v143, v145
	v_pk_add_f32 v[142:143], v[148:149], v[142:143]
	v_mov_b32_e32 v148, v139
	v_mov_b32_e32 v149, v140
	v_mov_b32_e32 v139, v141
	v_pk_add_f32 v[138:139], v[148:149], v[138:139]
	v_pk_add_f32 v[142:143], v[142:143], v[142:143] op_sel:[0,1] op_sel_hi:[1,0]
	v_pk_add_f32 v[138:139], v[138:139], v[138:139] op_sel:[0,1] op_sel_hi:[1,0]
	v_mov_b32_e32 v143, v142
	v_mov_b32_e32 v139, v138
	s_nop 0
	v_permlane16_swap_b32_e32 v142, v143
	v_permlane16_swap_b32_e32 v138, v139
	v_add_f32_e32 v143, v142, v143
	v_add_f32_e32 v142, v138, v139
	v_mov_b32_e32 v145, v143
	v_mov_b32_e32 v144, v142
	s_nop 0
	v_permlane32_swap_b32_e32 v143, v145
	v_permlane32_swap_b32_e32 v142, v144
	v_pk_add_f32 v[138:139], v[142:143], v[144:145]
	v_mov_b32_e32 v141, v136
	v_pk_fma_f32 v[138:139], v[138:139], s[4:5], v[182:183] op_sel_hi:[1,0,0]
	s_nop 0
	v_mul_f32_e32 v140, 0x4b800000, v139
	v_cmp_gt_f32_e64 s[46:47], s50, v139
	v_cmp_gt_f32_e32 vcc, s50, v138
	s_nop 0
	v_cndmask_b32_e64 v139, v139, v140, s[46:47]
	v_rsq_f32_e32 v139, v139
	s_nop 0
	v_mul_f32_e32 v140, 0x45800000, v139
	v_cndmask_b32_e64 v139, v139, v140, s[46:47]
; __device__ __forceinline__ unsigned cvtpk(float lo, float hi) { f32x2_t v = {lo, hi}; bf16x2_t b = __builtin_convertvector(v, bf16x2_t); return __builtin_bit_cast(unsigned, b); }
;     __device__ __forceinline__ void operator()(const AccT& acc, const Unit& u, int wr, int wc, int fr, int fq) const {
;     ...
;         for (int ai = 0; ai < 2; ++ai)
; #pragma unroll
;             for (int m = 0; m < 4; ++m) { const int row = row0 + ai * 128 + m * 16; const float rs = rsv[ai][m];
; #pragma unroll
;                 for (int bj = 0; bj < 2; ++bj) { float a[8];
; #pragma unroll
;                     for (int n = 0; n < 2; ++n)
; #pragma unroll
;                         for (int j = 0; j < 4; ++j) { const float x_ = acc[ai][bj][m][n][j]; a[n * 4 + j] = ACT ? __builtin_amdgcn_rcpf(1.0f + __builtin_amdgcn_exp2f(x_ * (-rs * LOG2E))) : x_ * rs; }
;                     u32x4 w; w.x = cvtpk(a[0], a[1]); w.y = cvtpk(a[2], a[3]); w.z = cvtpk(a[4], a[5]); w.w = cvtpk(a[6], a[7]);
;                     *(u32x4*)(O + (size_t)row * ldc + col0 + bj * 128) = w; } }
	v_mul_f32_e32 v140, 0x4b800000, v138
	v_cndmask_b32_e32 v138, v138, v140, vcc
	v_rsq_f32_e32 v138, v138
	s_nop 0
	v_mul_f32_e32 v140, 0x45800000, v138
	v_cndmask_b32_e32 v138, v138, v140, vcc
	v_mov_b32_e32 v140, v135
	v_mov_b32_e32 v135, v137
	v_pk_add_f32 v[134:135], v[140:141], v[134:135]
	v_mov_b32_e32 v140, v131
	v_mov_b32_e32 v141, v132
	v_mov_b32_e32 v131, v133
	v_pk_add_f32 v[130:131], v[140:141], v[130:131]
	v_pk_add_f32 v[134:135], v[134:135], v[134:135] op_sel:[0,1] op_sel_hi:[1,0]
	v_pk_add_f32 v[130:131], v[130:131], v[130:131] op_sel:[0,1] op_sel_hi:[1,0]
	v_mov_b32_e32 v135, v134
	v_mov_b32_e32 v131, v130
	s_nop 0
	v_permlane16_swap_b32_e32 v134, v135
	v_permlane16_swap_b32_e32 v130, v131
	v_add_f32_e32 v135, v134, v135
	v_add_f32_e32 v134, v130, v131
	v_mov_b32_e32 v137, v135
	v_mov_b32_e32 v136, v134
	s_nop 0
	v_permlane32_swap_b32_e32 v135, v137
	v_permlane32_swap_b32_e32 v134, v136
	v_pk_add_f32 v[130:131], v[134:135], v[136:137]
	v_mul_f32_e32 v136, 0xbfb8aa3b, v169
	v_pk_fma_f32 v[130:131], v[130:131], s[4:5], v[182:183] op_sel_hi:[1,0,0]
	v_mul_f32_e32 v126, v126, v136
	v_mul_f32_e32 v132, 0x4b800000, v131
	v_cmp_gt_f32_e64 s[46:47], s50, v131
	v_mul_f32_e32 v127, v127, v136
	v_mul_f32_e32 v128, v128, v136
	v_cndmask_b32_e64 v131, v131, v132, s[46:47]
	v_rsq_f32_e32 v131, v131
	v_mul_f32_e32 v129, v129, v136
	v_pk_mul_f32 v[122:123], v[122:123], v[136:137] op_sel_hi:[1,0]
	v_mul_f32_e32 v132, 0x45800000, v131
	v_exp_f32_e32 v126, v126
	v_exp_f32_e32 v127, v127
	v_exp_f32_e32 v128, v128
	v_exp_f32_e32 v129, v129
	v_exp_f32_e32 v122, v122
	v_exp_f32_e32 v123, v123
	v_pk_mul_f32 v[124:125], v[124:125], v[136:137] op_sel_hi:[1,0]
	v_cmp_gt_f32_e32 vcc, s50, v130
	v_cndmask_b32_e64 v131, v131, v132, s[46:47]
	v_mul_f32_e32 v132, 0x4b800000, v130
	v_exp_f32_e32 v124, v124
	v_exp_f32_e32 v125, v125
	v_cndmask_b32_e32 v130, v130, v132, vcc
	v_rsq_f32_e32 v130, v130
	v_pk_add_f32 v[126:127], v[210:211], v[126:127] op_sel_hi:[0,1]
	v_pk_add_f32 v[128:129], v[210:211], v[128:129] op_sel_hi:[0,1]
	v_pk_add_f32 v[122:123], v[210:211], v[122:123] op_sel_hi:[0,1]
	v_rcp_f32_e32 v126, v126
	v_rcp_f32_e32 v127, v127
	v_rcp_f32_e32 v128, v128
	v_rcp_f32_e32 v129, v129
	v_rcp_f32_e32 v122, v122
	v_rcp_f32_e32 v123, v123
	v_pk_add_f32 v[124:125], v[210:211], v[124:125] op_sel_hi:[0,1]
	s_nop 0
	v_rcp_f32_e32 v124, v124
	v_rcp_f32_e32 v125, v125
	v_mul_f32_e32 v114, v114, v136
	v_mul_f32_e32 v132, 0x45800000, v130
	v_exp_f32_e32 v114, v114
	v_cndmask_b32_e32 v130, v130, v132, vcc
	v_lshl_or_b32 v132, s14, 8, v186
	v_ashrrev_i32_e32 v133, 31, v132
	v_cvt_pk_bf16_f32 v126, v126, v127
	v_cvt_pk_bf16_f32 v127, v128, v129
	v_cvt_pk_bf16_f32 v128, v122, v123
	v_mov_b64_e32 v[122:123], s[70:71]
	v_cvt_pk_bf16_f32 v129, v124, v125
	v_mad_i64_i32 v[134:135], s[0:1], v180, s5, v[122:123]
	v_lshlrev_b64 v[124:125], 1, v[132:133]
	v_lshl_add_u64 v[132:133], v[134:135], 0, v[124:125]
	v_add_f32_e32 v114, 1.0, v114
	global_store_dwordx4 v[132:133], v[126:129], off
	v_pk_mul_f32 v[118:119], v[118:119], v[136:137] op_sel_hi:[1,0]
	v_rcp_f32_e32 v126, v114
	v_mul_f32_e32 v114, v115, v136
	v_exp_f32_e32 v114, v114
	v_pk_mul_f32 v[120:121], v[120:121], v[136:137] op_sel_hi:[1,0]
	v_exp_f32_e32 v118, v118
	v_add_f32_e32 v114, 1.0, v114
	v_rcp_f32_e32 v127, v114
	v_mul_f32_e32 v114, v116, v136
	v_exp_f32_e32 v114, v114
	v_exp_f32_e32 v119, v119
	v_exp_f32_e32 v120, v120
	v_exp_f32_e32 v121, v121
	v_add_f32_e32 v114, 1.0, v114
	v_rcp_f32_e32 v128, v114
	v_mul_f32_e32 v114, v117, v136
	v_exp_f32_e32 v114, v114
	v_pk_add_f32 v[118:119], v[210:211], v[118:119] op_sel_hi:[0,1]
	v_pk_add_f32 v[120:121], v[210:211], v[120:121] op_sel_hi:[0,1]
	v_add_f32_e32 v114, 1.0, v114
	v_rcp_f32_e32 v118, v118
	v_rcp_f32_e32 v119, v119
	v_rcp_f32_e32 v120, v120
	v_rcp_f32_e32 v121, v121
	v_rcp_f32_e32 v117, v114
	v_cvt_pk_bf16_f32 v114, v118, v119
	v_cvt_pk_bf16_f32 v116, v126, v127
	v_cvt_pk_bf16_f32 v115, v120, v121
	v_cvt_pk_bf16_f32 v117, v128, v117
	global_store_dwordx4 v[132:133], v[114:117], off offset:256
	s_and_b64 vcc, exec, s[44:45]
	s_nop 0
	v_mul_f32_e32 v114, 0xbfb8aa3b, v167
	v_mul_f32_e32 v106, v106, v114
	v_exp_f32_e32 v106, v106
	v_pk_mul_f32 v[110:111], v[110:111], v[114:115] op_sel_hi:[1,0]
	s_nop 0
	v_exp_f32_e32 v110, v110
	v_add_f32_e32 v106, 1.0, v106
	v_rcp_f32_e32 v115, v106
	v_mul_f32_e32 v106, v107, v114
	v_exp_f32_e32 v106, v106
	v_exp_f32_e32 v111, v111
	v_pk_mul_f32 v[112:113], v[112:113], v[114:115] op_sel_hi:[1,0]
	v_add_f32_e32 v106, 1.0, v106
	v_rcp_f32_e32 v116, v106
	v_mul_f32_e32 v106, v108, v114
	v_exp_f32_e32 v106, v106
	v_exp_f32_e32 v112, v112
	v_exp_f32_e32 v113, v113
	v_add_f32_e32 v110, 1.0, v110
	v_add_f32_e32 v106, 1.0, v106
	v_rcp_f32_e32 v117, v106
	v_mul_f32_e32 v106, v109, v114
	v_exp_f32_e32 v106, v106
	v_add_f32_e32 v111, 1.0, v111
	v_rcp_f32_e32 v110, v110
	v_rcp_f32_e32 v111, v111
	v_pk_add_f32 v[112:113], v[210:211], v[112:113] op_sel_hi:[0,1]
	v_add_f32_e32 v106, 1.0, v106
	v_mul_f32_e32 v98, v98, v114
	v_rcp_f32_e32 v112, v112
	v_rcp_f32_e32 v113, v113
	v_rcp_f32_e32 v109, v106
	v_exp_f32_e32 v98, v98
	v_cvt_pk_bf16_f32 v106, v110, v111
	v_mad_i64_i32 v[110:111], s[0:1], v178, s5, v[122:123]
	v_cvt_pk_bf16_f32 v107, v112, v113
	v_cvt_pk_bf16_f32 v108, v115, v116
	v_cvt_pk_bf16_f32 v109, v117, v109
	v_lshl_add_u64 v[110:111], v[110:111], 0, v[124:125]
	v_add_f32_e32 v98, 1.0, v98
	global_store_dwordx4 v[110:111], v[106:109], off
	v_pk_mul_f32 v[102:103], v[102:103], v[114:115] op_sel_hi:[1,0]
	v_rcp_f32_e32 v106, v98
	v_mul_f32_e32 v98, v99, v114
	v_exp_f32_e32 v98, v98
	v_pk_mul_f32 v[104:105], v[104:105], v[114:115] op_sel_hi:[1,0]
; __device__ __forceinline__ unsigned cvtpk(float lo, float hi) { f32x2_t v = {lo, hi}; bf16x2_t b = __builtin_convertvector(v, bf16x2_t); return __builtin_bit_cast(unsigned, b); }
;     __device__ __forceinline__ void operator()(const AccT& acc, const Unit& u, int wr, int wc, int fr, int fq) const {
;     ...
;         for (int ai = 0; ai < 2; ++ai)
; #pragma unroll
;             for (int m = 0; m < 4; ++m) { const int row = row0 + ai * 128 + m * 16; const float rs = rsv[ai][m];
; #pragma unroll
;                 for (int bj = 0; bj < 2; ++bj) { float a[8];
; #pragma unroll
;                     for (int n = 0; n < 2; ++n)
; #pragma unroll
;                         for (int j = 0; j < 4; ++j) { const float x_ = acc[ai][bj][m][n][j]; a[n * 4 + j] = ACT ? __builtin_amdgcn_rcpf(1.0f + __builtin_amdgcn_exp2f(x_ * (-rs * LOG2E))) : x_ * rs; }
;                     u32x4 w; w.x = cvtpk(a[0], a[1]); w.y = cvtpk(a[2], a[3]); w.z = cvtpk(a[4], a[5]); w.w = cvtpk(a[6], a[7]);
;                     *(u32x4*)(O + (size_t)row * ldc + col0 + bj * 128) = w; } }
	v_exp_f32_e32 v102, v102
	v_add_f32_e32 v98, 1.0, v98
	v_rcp_f32_e32 v107, v98
	v_mul_f32_e32 v98, v100, v114
	v_exp_f32_e32 v98, v98
	v_exp_f32_e32 v103, v103
	v_exp_f32_e32 v104, v104
	v_exp_f32_e32 v105, v105
	v_add_f32_e32 v98, 1.0, v98
	v_rcp_f32_e32 v108, v98
	v_mul_f32_e32 v98, v101, v114
	v_exp_f32_e32 v98, v98
	v_pk_add_f32 v[102:103], v[210:211], v[102:103] op_sel_hi:[0,1]
	v_pk_add_f32 v[104:105], v[210:211], v[104:105] op_sel_hi:[0,1]
	v_add_f32_e32 v98, 1.0, v98
	v_rcp_f32_e32 v102, v102
	v_rcp_f32_e32 v103, v103
	v_rcp_f32_e32 v104, v104
	v_rcp_f32_e32 v105, v105
	v_rcp_f32_e32 v101, v98
	v_cvt_pk_bf16_f32 v98, v102, v103
	v_cvt_pk_bf16_f32 v100, v106, v107
	v_cvt_pk_bf16_f32 v99, v104, v105
	v_cvt_pk_bf16_f32 v101, v108, v101
	global_store_dwordx4 v[110:111], v[98:101], off offset:256
	s_nop 1
	v_mul_f32_e32 v98, 0xbfb8aa3b, v147
	v_mul_f32_e32 v90, v90, v98
	v_exp_f32_e32 v90, v90
	v_pk_mul_f32 v[94:95], v[94:95], v[98:99] op_sel_hi:[1,0]
	s_nop 0
	v_exp_f32_e32 v94, v94
	v_add_f32_e32 v90, 1.0, v90
	v_rcp_f32_e32 v99, v90
	v_mul_f32_e32 v90, v91, v98
	v_exp_f32_e32 v90, v90
	v_exp_f32_e32 v95, v95
	v_pk_mul_f32 v[96:97], v[96:97], v[98:99] op_sel_hi:[1,0]
	v_add_f32_e32 v90, 1.0, v90
	v_rcp_f32_e32 v100, v90
	v_mul_f32_e32 v90, v92, v98
	v_exp_f32_e32 v90, v90
	v_exp_f32_e32 v96, v96
	v_exp_f32_e32 v97, v97
	v_add_f32_e32 v94, 1.0, v94
	v_add_f32_e32 v90, 1.0, v90
	v_rcp_f32_e32 v101, v90
	v_mul_f32_e32 v90, v93, v98
	v_exp_f32_e32 v90, v90
	v_add_f32_e32 v95, 1.0, v95
	v_rcp_f32_e32 v94, v94
	v_rcp_f32_e32 v95, v95
	v_pk_add_f32 v[96:97], v[210:211], v[96:97] op_sel_hi:[0,1]
	v_add_f32_e32 v90, 1.0, v90
	v_mul_f32_e32 v82, v82, v98
	v_rcp_f32_e32 v96, v96
	v_rcp_f32_e32 v97, v97
	v_rcp_f32_e32 v93, v90
	v_exp_f32_e32 v82, v82
	v_cvt_pk_bf16_f32 v90, v94, v95
	v_mad_i64_i32 v[94:95], s[0:1], v176, s5, v[122:123]
	v_cvt_pk_bf16_f32 v91, v96, v97
	v_cvt_pk_bf16_f32 v92, v99, v100
	v_cvt_pk_bf16_f32 v93, v101, v93
	v_lshl_add_u64 v[94:95], v[94:95], 0, v[124:125]
	v_add_f32_e32 v82, 1.0, v82
	global_store_dwordx4 v[94:95], v[90:93], off
	v_pk_mul_f32 v[86:87], v[86:87], v[98:99] op_sel_hi:[1,0]
	v_rcp_f32_e32 v90, v82
	v_mul_f32_e32 v82, v83, v98
	v_exp_f32_e32 v82, v82
	v_pk_mul_f32 v[88:89], v[88:89], v[98:99] op_sel_hi:[1,0]
	v_exp_f32_e32 v86, v86
	v_add_f32_e32 v82, 1.0, v82
	v_rcp_f32_e32 v91, v82
	v_mul_f32_e32 v82, v84, v98
	v_exp_f32_e32 v82, v82
	v_exp_f32_e32 v87, v87
	v_exp_f32_e32 v88, v88
	v_exp_f32_e32 v89, v89
	v_add_f32_e32 v82, 1.0, v82
	v_rcp_f32_e32 v92, v82
	v_mul_f32_e32 v82, v85, v98
	v_exp_f32_e32 v82, v82
	v_pk_add_f32 v[86:87], v[210:211], v[86:87] op_sel_hi:[0,1]
	v_pk_add_f32 v[88:89], v[210:211], v[88:89] op_sel_hi:[0,1]
	v_add_f32_e32 v82, 1.0, v82
	v_rcp_f32_e32 v86, v86
	v_rcp_f32_e32 v87, v87
	v_rcp_f32_e32 v88, v88
	v_rcp_f32_e32 v89, v89
	v_rcp_f32_e32 v85, v82
	v_cvt_pk_bf16_f32 v82, v86, v87
	v_cvt_pk_bf16_f32 v84, v90, v91
	v_cvt_pk_bf16_f32 v83, v88, v89
	v_cvt_pk_bf16_f32 v85, v92, v85
	global_store_dwordx4 v[94:95], v[82:85], off offset:256
	s_nop 1
	v_mul_f32_e32 v82, 0xbfb8aa3b, v146
	v_mul_f32_e32 v74, v74, v82
	v_exp_f32_e32 v74, v74
	v_pk_mul_f32 v[78:79], v[78:79], v[82:83] op_sel_hi:[1,0]
	s_nop 0
	v_exp_f32_e32 v78, v78
	v_add_f32_e32 v74, 1.0, v74
	v_rcp_f32_e32 v83, v74
	v_mul_f32_e32 v74, v75, v82
	v_exp_f32_e32 v74, v74
	v_exp_f32_e32 v79, v79
	v_pk_mul_f32 v[80:81], v[80:81], v[82:83] op_sel_hi:[1,0]
	v_add_f32_e32 v74, 1.0, v74
	v_rcp_f32_e32 v84, v74
	v_mul_f32_e32 v74, v76, v82
	v_exp_f32_e32 v74, v74
	v_exp_f32_e32 v80, v80
	v_exp_f32_e32 v81, v81
	v_add_f32_e32 v78, 1.0, v78
	v_add_f32_e32 v74, 1.0, v74
	v_rcp_f32_e32 v85, v74
	v_mul_f32_e32 v74, v77, v82
	v_exp_f32_e32 v74, v74
	v_add_f32_e32 v79, 1.0, v79
	v_rcp_f32_e32 v78, v78
	v_rcp_f32_e32 v79, v79
	v_pk_add_f32 v[80:81], v[210:211], v[80:81] op_sel_hi:[0,1]
	v_add_f32_e32 v74, 1.0, v74
	v_mul_f32_e32 v66, v66, v82
	v_rcp_f32_e32 v80, v80
	v_rcp_f32_e32 v81, v81
	v_rcp_f32_e32 v77, v74
	v_exp_f32_e32 v66, v66
	v_cvt_pk_bf16_f32 v74, v78, v79
	v_mad_i64_i32 v[78:79], s[0:1], v174, s5, v[122:123]
	v_cvt_pk_bf16_f32 v75, v80, v81
	v_cvt_pk_bf16_f32 v76, v83, v84
	v_cvt_pk_bf16_f32 v77, v85, v77
	v_lshl_add_u64 v[78:79], v[78:79], 0, v[124:125]
	v_add_f32_e32 v66, 1.0, v66
	global_store_dwordx4 v[78:79], v[74:77], off
	v_pk_mul_f32 v[70:71], v[70:71], v[82:83] op_sel_hi:[1,0]
	v_rcp_f32_e32 v74, v66
	v_mul_f32_e32 v66, v67, v82
	v_exp_f32_e32 v66, v66
	v_pk_mul_f32 v[72:73], v[72:73], v[82:83] op_sel_hi:[1,0]
	v_exp_f32_e32 v70, v70
	v_add_f32_e32 v66, 1.0, v66
	v_rcp_f32_e32 v75, v66
	v_mul_f32_e32 v66, v68, v82
	v_exp_f32_e32 v66, v66
	v_exp_f32_e32 v71, v71
	v_exp_f32_e32 v72, v72
	v_exp_f32_e32 v73, v73
	v_add_f32_e32 v66, 1.0, v66
	v_rcp_f32_e32 v76, v66
	v_mul_f32_e32 v66, v69, v82
	v_exp_f32_e32 v66, v66
	v_pk_add_f32 v[70:71], v[210:211], v[70:71] op_sel_hi:[0,1]
	v_pk_add_f32 v[72:73], v[210:211], v[72:73] op_sel_hi:[0,1]
	v_add_f32_e32 v66, 1.0, v66
	v_rcp_f32_e32 v70, v70
	v_rcp_f32_e32 v71, v71
	v_rcp_f32_e32 v72, v72
	v_rcp_f32_e32 v73, v73
	v_rcp_f32_e32 v69, v66
	v_cvt_pk_bf16_f32 v66, v70, v71
	v_cvt_pk_bf16_f32 v68, v74, v75
	v_cvt_pk_bf16_f32 v67, v72, v73
	v_cvt_pk_bf16_f32 v69, v76, v69
	global_store_dwordx4 v[78:79], v[66:69], off offset:256
	s_nop 1
	v_mul_f32_e32 v66, 0xbfb8aa3b, v139
	v_mul_f32_e32 v58, v58, v66
	v_exp_f32_e32 v58, v58
	v_pk_mul_f32 v[62:63], v[62:63], v[66:67] op_sel_hi:[1,0]
	s_nop 0
	v_exp_f32_e32 v62, v62
	v_add_f32_e32 v58, 1.0, v58
	v_rcp_f32_e32 v67, v58
	v_mul_f32_e32 v58, v59, v66
	v_exp_f32_e32 v58, v58
	v_exp_f32_e32 v63, v63
	v_pk_mul_f32 v[64:65], v[64:65], v[66:67] op_sel_hi:[1,0]
; __device__ __forceinline__ unsigned cvtpk(float lo, float hi) { f32x2_t v = {lo, hi}; bf16x2_t b = __builtin_convertvector(v, bf16x2_t); return __builtin_bit_cast(unsigned, b); }
;     __device__ __forceinline__ void operator()(const AccT& acc, const Unit& u, int wr, int wc, int fr, int fq) const {
;     ...
;         for (int ai = 0; ai < 2; ++ai)
; #pragma unroll
;             for (int m = 0; m < 4; ++m) { const int row = row0 + ai * 128 + m * 16; const float rs = rsv[ai][m];
; #pragma unroll
;                 for (int bj = 0; bj < 2; ++bj) { float a[8];
; #pragma unroll
;                     for (int n = 0; n < 2; ++n)
; #pragma unroll
;                         for (int j = 0; j < 4; ++j) { const float x_ = acc[ai][bj][m][n][j]; a[n * 4 + j] = ACT ? __builtin_amdgcn_rcpf(1.0f + __builtin_amdgcn_exp2f(x_ * (-rs * LOG2E))) : x_ * rs; }
;                     u32x4 w; w.x = cvtpk(a[0], a[1]); w.y = cvtpk(a[2], a[3]); w.z = cvtpk(a[4], a[5]); w.w = cvtpk(a[6], a[7]);
;                     *(u32x4*)(O + (size_t)row * ldc + col0 + bj * 128) = w; } }
	v_add_f32_e32 v58, 1.0, v58
	v_rcp_f32_e32 v68, v58
	v_mul_f32_e32 v58, v60, v66
	v_exp_f32_e32 v58, v58
	v_exp_f32_e32 v64, v64
	v_exp_f32_e32 v65, v65
	v_add_f32_e32 v62, 1.0, v62
	v_add_f32_e32 v58, 1.0, v58
	v_rcp_f32_e32 v69, v58
	v_mul_f32_e32 v58, v61, v66
	v_exp_f32_e32 v58, v58
	v_add_f32_e32 v63, 1.0, v63
	v_rcp_f32_e32 v62, v62
	v_rcp_f32_e32 v63, v63
	v_pk_add_f32 v[64:65], v[210:211], v[64:65] op_sel_hi:[0,1]
	v_add_f32_e32 v58, 1.0, v58
	v_mul_f32_e32 v50, v50, v66
	v_rcp_f32_e32 v64, v64
	v_rcp_f32_e32 v65, v65
	v_rcp_f32_e32 v61, v58
	v_exp_f32_e32 v50, v50
	v_cvt_pk_bf16_f32 v58, v62, v63
	v_mad_i64_i32 v[62:63], s[0:1], v172, s5, v[122:123]
	v_cvt_pk_bf16_f32 v59, v64, v65
	v_cvt_pk_bf16_f32 v60, v67, v68
	v_cvt_pk_bf16_f32 v61, v69, v61
	v_lshl_add_u64 v[62:63], v[62:63], 0, v[124:125]
	v_add_f32_e32 v50, 1.0, v50
	global_store_dwordx4 v[62:63], v[58:61], off
	v_pk_mul_f32 v[54:55], v[54:55], v[66:67] op_sel_hi:[1,0]
	v_rcp_f32_e32 v58, v50
	v_mul_f32_e32 v50, v51, v66
	v_exp_f32_e32 v50, v50
	v_pk_mul_f32 v[56:57], v[56:57], v[66:67] op_sel_hi:[1,0]
	v_exp_f32_e32 v54, v54
	v_add_f32_e32 v50, 1.0, v50
	v_rcp_f32_e32 v59, v50
	v_mul_f32_e32 v50, v52, v66
	v_exp_f32_e32 v50, v50
	v_exp_f32_e32 v55, v55
	v_exp_f32_e32 v56, v56
	v_exp_f32_e32 v57, v57
	v_add_f32_e32 v50, 1.0, v50
	v_rcp_f32_e32 v60, v50
	v_mul_f32_e32 v50, v53, v66
	v_exp_f32_e32 v50, v50
	v_pk_add_f32 v[54:55], v[210:211], v[54:55] op_sel_hi:[0,1]
	v_pk_add_f32 v[56:57], v[210:211], v[56:57] op_sel_hi:[0,1]
	v_add_f32_e32 v50, 1.0, v50
	v_rcp_f32_e32 v54, v54
	v_rcp_f32_e32 v55, v55
	v_rcp_f32_e32 v56, v56
	v_rcp_f32_e32 v57, v57
	v_rcp_f32_e32 v53, v50
	v_cvt_pk_bf16_f32 v50, v54, v55
	v_cvt_pk_bf16_f32 v52, v58, v59
	v_cvt_pk_bf16_f32 v51, v56, v57
	v_cvt_pk_bf16_f32 v53, v60, v53
	global_store_dwordx4 v[62:63], v[50:53], off offset:256
	s_nop 1
	v_mul_f32_e32 v50, 0xbfb8aa3b, v138
	v_mul_f32_e32 v42, v42, v50
	v_exp_f32_e32 v42, v42
	v_pk_mul_f32 v[46:47], v[46:47], v[50:51] op_sel_hi:[1,0]
	s_nop 0
	v_exp_f32_e32 v46, v46
	v_add_f32_e32 v42, 1.0, v42
	v_rcp_f32_e32 v51, v42
	v_mul_f32_e32 v42, v43, v50
	v_exp_f32_e32 v42, v42
	v_exp_f32_e32 v47, v47
	v_pk_mul_f32 v[48:49], v[48:49], v[50:51] op_sel_hi:[1,0]
	v_add_f32_e32 v42, 1.0, v42
	v_rcp_f32_e32 v52, v42
	v_mul_f32_e32 v42, v44, v50
	v_exp_f32_e32 v42, v42
	v_exp_f32_e32 v48, v48
	v_exp_f32_e32 v49, v49
	v_add_f32_e32 v46, 1.0, v46
	v_add_f32_e32 v42, 1.0, v42
	v_rcp_f32_e32 v53, v42
	v_mul_f32_e32 v42, v45, v50
	v_exp_f32_e32 v42, v42
	v_add_f32_e32 v47, 1.0, v47
	v_rcp_f32_e32 v46, v46
	v_rcp_f32_e32 v47, v47
	v_pk_add_f32 v[48:49], v[210:211], v[48:49] op_sel_hi:[0,1]
	v_add_f32_e32 v42, 1.0, v42
	v_mul_f32_e32 v34, v34, v50
	v_rcp_f32_e32 v48, v48
	v_rcp_f32_e32 v49, v49
	v_rcp_f32_e32 v45, v42
	v_exp_f32_e32 v34, v34
	v_cvt_pk_bf16_f32 v42, v46, v47
	v_mad_i64_i32 v[46:47], s[0:1], v170, s5, v[122:123]
	v_cvt_pk_bf16_f32 v43, v48, v49
	v_cvt_pk_bf16_f32 v44, v51, v52
	v_cvt_pk_bf16_f32 v45, v53, v45
	v_lshl_add_u64 v[46:47], v[46:47], 0, v[124:125]
	v_add_f32_e32 v34, 1.0, v34
	global_store_dwordx4 v[46:47], v[42:45], off
	v_pk_mul_f32 v[38:39], v[38:39], v[50:51] op_sel_hi:[1,0]
	v_rcp_f32_e32 v42, v34
	v_mul_f32_e32 v34, v35, v50
	v_exp_f32_e32 v34, v34
	v_pk_mul_f32 v[40:41], v[40:41], v[50:51] op_sel_hi:[1,0]
	v_exp_f32_e32 v38, v38
	v_add_f32_e32 v34, 1.0, v34
	v_rcp_f32_e32 v43, v34
	v_mul_f32_e32 v34, v36, v50
	v_exp_f32_e32 v34, v34
	v_exp_f32_e32 v39, v39
	v_exp_f32_e32 v40, v40
	v_exp_f32_e32 v41, v41
	v_add_f32_e32 v34, 1.0, v34
	v_rcp_f32_e32 v44, v34
	v_mul_f32_e32 v34, v37, v50
	v_exp_f32_e32 v34, v34
	v_pk_add_f32 v[38:39], v[210:211], v[38:39] op_sel_hi:[0,1]
	v_pk_add_f32 v[40:41], v[210:211], v[40:41] op_sel_hi:[0,1]
	v_add_f32_e32 v34, 1.0, v34
	v_rcp_f32_e32 v38, v38
	v_rcp_f32_e32 v39, v39
	v_rcp_f32_e32 v40, v40
	v_rcp_f32_e32 v41, v41
	v_rcp_f32_e32 v37, v34
	v_cvt_pk_bf16_f32 v34, v38, v39
	v_cvt_pk_bf16_f32 v36, v42, v43
	v_cvt_pk_bf16_f32 v35, v40, v41
	v_cvt_pk_bf16_f32 v37, v44, v37
	global_store_dwordx4 v[46:47], v[34:37], off offset:256
	s_nop 1
	v_mul_f32_e32 v34, 0xbfb8aa3b, v131
	v_mul_f32_e32 v26, v26, v34
	v_exp_f32_e32 v26, v26
	v_pk_mul_f32 v[30:31], v[30:31], v[34:35] op_sel_hi:[1,0]
	s_nop 0
	v_exp_f32_e32 v30, v30
	v_add_f32_e32 v26, 1.0, v26
; __device__ __forceinline__ unsigned cvtpk(float lo, float hi) { f32x2_t v = {lo, hi}; bf16x2_t b = __builtin_convertvector(v, bf16x2_t); return __builtin_bit_cast(unsigned, b); }
; #define PG8_BAR __builtin_amdgcn_s_barrier()
; template <class Epi, class Sched>
; __device__ __forceinline__ void gemm_phase(LAS unsigned char* lds, const Gemm g, const Sched& S, const Epi& E) {
;     ...
;         if (wr == 0) PG8_BAR;
;         E(acc, cur, wr, wc, fr, fq);
;         if (!has_next) break;
; #pragma unroll
;         for (int a = 0; a < 2; ++a)
; #pragma unroll
;             for (int b = 0; b < 2; ++b)
; #pragma unroll
;                 for (int m = 0; m < 4; ++m)
; #pragma unroll
;                     for (int n = 0; n < 2; ++n) acc[a][b][m][n] = (f32x4){0.f, 0.f, 0.f, 0.f};
;         cur = nxt; cA = nA; cB = nB; ++ui;
;         if (wr == 1) PG8_BAR;
;     }
;     __device__ __forceinline__ void operator()(const AccT& acc, const Unit& u, int wr, int wc, int fr, int fq) const {
;     ...
;         for (int ai = 0; ai < 2; ++ai)
; #pragma unroll
;             for (int m = 0; m < 4; ++m) { const int row = row0 + ai * 128 + m * 16; const float rs = rsv[ai][m];
; #pragma unroll
;                 for (int bj = 0; bj < 2; ++bj) { float a[8];
; #pragma unroll
;                     for (int n = 0; n < 2; ++n)
; #pragma unroll
;                         for (int j = 0; j < 4; ++j) { const float x_ = acc[ai][bj][m][n][j]; a[n * 4 + j] = ACT ? __builtin_amdgcn_rcpf(1.0f + __builtin_amdgcn_exp2f(x_ * (-rs * LOG2E))) : x_ * rs; }
;                     u32x4 w; w.x = cvtpk(a[0], a[1]); w.y = cvtpk(a[2], a[3]); w.z = cvtpk(a[4], a[5]); w.w = cvtpk(a[6], a[7]);
;                     *(u32x4*)(O + (size_t)row * ldc + col0 + bj * 128) = w; } }
	v_rcp_f32_e32 v35, v26
	v_mul_f32_e32 v26, v27, v34
	v_exp_f32_e32 v26, v26
	v_exp_f32_e32 v31, v31
	v_pk_mul_f32 v[32:33], v[32:33], v[34:35] op_sel_hi:[1,0]
	v_add_f32_e32 v26, 1.0, v26
	v_rcp_f32_e32 v36, v26
	v_mul_f32_e32 v26, v28, v34
	v_exp_f32_e32 v26, v26
	v_exp_f32_e32 v32, v32
	v_exp_f32_e32 v33, v33
	v_add_f32_e32 v30, 1.0, v30
	v_add_f32_e32 v26, 1.0, v26
	v_rcp_f32_e32 v37, v26
	v_mul_f32_e32 v26, v29, v34
	v_exp_f32_e32 v26, v26
	v_add_f32_e32 v31, 1.0, v31
	v_rcp_f32_e32 v30, v30
	v_rcp_f32_e32 v31, v31
	v_pk_add_f32 v[32:33], v[210:211], v[32:33] op_sel_hi:[0,1]
	v_add_f32_e32 v26, 1.0, v26
	v_mul_f32_e32 v18, v18, v34
	v_rcp_f32_e32 v32, v32
	v_rcp_f32_e32 v33, v33
	v_rcp_f32_e32 v29, v26
	v_exp_f32_e32 v18, v18
	v_cvt_pk_bf16_f32 v26, v30, v31
	v_mad_i64_i32 v[30:31], s[0:1], v168, s5, v[122:123]
	v_cvt_pk_bf16_f32 v27, v32, v33
	v_cvt_pk_bf16_f32 v28, v35, v36
	v_cvt_pk_bf16_f32 v29, v37, v29
	v_lshl_add_u64 v[30:31], v[30:31], 0, v[124:125]
	v_add_f32_e32 v18, 1.0, v18
	global_store_dwordx4 v[30:31], v[26:29], off
	v_pk_mul_f32 v[22:23], v[22:23], v[34:35] op_sel_hi:[1,0]
	v_rcp_f32_e32 v26, v18
	v_mul_f32_e32 v18, v19, v34
	v_exp_f32_e32 v18, v18
	v_pk_mul_f32 v[24:25], v[24:25], v[34:35] op_sel_hi:[1,0]
	v_exp_f32_e32 v22, v22
	v_add_f32_e32 v18, 1.0, v18
	v_rcp_f32_e32 v27, v18
	v_mul_f32_e32 v18, v20, v34
	v_exp_f32_e32 v18, v18
	v_exp_f32_e32 v23, v23
	v_exp_f32_e32 v24, v24
	v_exp_f32_e32 v25, v25
	v_add_f32_e32 v18, 1.0, v18
	v_rcp_f32_e32 v28, v18
	v_mul_f32_e32 v18, v21, v34
	v_exp_f32_e32 v18, v18
	v_pk_add_f32 v[22:23], v[210:211], v[22:23] op_sel_hi:[0,1]
	v_pk_add_f32 v[24:25], v[210:211], v[24:25] op_sel_hi:[0,1]
	v_add_f32_e32 v18, 1.0, v18
	v_rcp_f32_e32 v22, v22
	v_rcp_f32_e32 v23, v23
	v_rcp_f32_e32 v24, v24
	v_rcp_f32_e32 v25, v25
	v_rcp_f32_e32 v21, v18
	v_cvt_pk_bf16_f32 v18, v22, v23
	v_cvt_pk_bf16_f32 v20, v26, v27
	v_cvt_pk_bf16_f32 v19, v24, v25
	v_cvt_pk_bf16_f32 v21, v28, v21
	global_store_dwordx4 v[30:31], v[18:21], off offset:256
	s_nop 1
	v_mul_f32_e32 v18, 0xbfb8aa3b, v130
	v_mul_f32_e32 v10, v10, v18
	v_exp_f32_e32 v10, v10
	v_pk_mul_f32 v[14:15], v[14:15], v[18:19] op_sel_hi:[1,0]
	s_nop 0
	v_exp_f32_e32 v14, v14
	v_add_f32_e32 v10, 1.0, v10
	v_rcp_f32_e32 v19, v10
	v_mul_f32_e32 v10, v11, v18
	v_exp_f32_e32 v10, v10
	v_exp_f32_e32 v15, v15
	v_pk_mul_f32 v[16:17], v[16:17], v[18:19] op_sel_hi:[1,0]
	v_add_f32_e32 v10, 1.0, v10
	v_rcp_f32_e32 v20, v10
	v_mul_f32_e32 v10, v12, v18
	v_exp_f32_e32 v10, v10
	v_exp_f32_e32 v16, v16
	v_exp_f32_e32 v17, v17
	v_add_f32_e32 v14, 1.0, v14
	v_add_f32_e32 v10, 1.0, v10
	v_rcp_f32_e32 v21, v10
	v_mul_f32_e32 v10, v13, v18
	v_exp_f32_e32 v10, v10
	v_add_f32_e32 v15, 1.0, v15
	v_rcp_f32_e32 v14, v14
	v_rcp_f32_e32 v15, v15
	v_pk_add_f32 v[16:17], v[210:211], v[16:17] op_sel_hi:[0,1]
	v_add_f32_e32 v10, 1.0, v10
	v_mul_f32_e32 v2, v2, v18
	v_rcp_f32_e32 v16, v16
	v_rcp_f32_e32 v17, v17
	v_rcp_f32_e32 v13, v10
	v_exp_f32_e32 v2, v2
	v_cvt_pk_bf16_f32 v10, v14, v15
	v_mad_i64_i32 v[14:15], s[0:1], v166, s5, v[122:123]
	v_cvt_pk_bf16_f32 v11, v16, v17
	v_cvt_pk_bf16_f32 v12, v19, v20
	v_cvt_pk_bf16_f32 v13, v21, v13
	v_lshl_add_u64 v[14:15], v[14:15], 0, v[124:125]
	v_add_f32_e32 v2, 1.0, v2
	global_store_dwordx4 v[14:15], v[10:13], off
	v_pk_mul_f32 v[6:7], v[6:7], v[18:19] op_sel_hi:[1,0]
	v_rcp_f32_e32 v10, v2
	v_mul_f32_e32 v2, v3, v18
	v_exp_f32_e32 v2, v2
	v_pk_mul_f32 v[8:9], v[8:9], v[18:19] op_sel_hi:[1,0]
	v_exp_f32_e32 v6, v6
	v_add_f32_e32 v2, 1.0, v2
	v_rcp_f32_e32 v11, v2
	v_mul_f32_e32 v2, v4, v18
	v_exp_f32_e32 v2, v2
	v_exp_f32_e32 v7, v7
	v_exp_f32_e32 v8, v8
	v_exp_f32_e32 v9, v9
	v_add_f32_e32 v2, 1.0, v2
	v_rcp_f32_e32 v12, v2
	v_mul_f32_e32 v2, v5, v18
	v_exp_f32_e32 v2, v2
	v_pk_add_f32 v[6:7], v[210:211], v[6:7] op_sel_hi:[0,1]
	v_pk_add_f32 v[8:9], v[210:211], v[8:9] op_sel_hi:[0,1]
	v_add_f32_e32 v2, 1.0, v2
	v_rcp_f32_e32 v6, v6
	v_rcp_f32_e32 v7, v7
	v_rcp_f32_e32 v8, v8
	v_rcp_f32_e32 v9, v9
	v_rcp_f32_e32 v5, v2
	v_cvt_pk_bf16_f32 v2, v6, v7
	v_cvt_pk_bf16_f32 v4, v10, v11
	v_cvt_pk_bf16_f32 v3, v8, v9
	v_cvt_pk_bf16_f32 v5, v12, v5
	s_mov_b64 s[0:1], -1
	global_store_dwordx4 v[14:15], v[2:5], off offset:256
	s_cbranch_vccnz .LBB0_1431
	s_andn2_b64 vcc, exec, s[62:63]
	s_cbranch_vccnz .LBB0_1430
	s_barrier
	s_branch .LBB0_1430

; __device__ __forceinline__ unsigned cvtpk(float lo, float hi) { f32x2_t v = {lo, hi}; bf16x2_t b = __builtin_convertvector(v, bf16x2_t); return __builtin_bit_cast(unsigned, b); }
; __device__ __forceinline__ float sigm_f(float g) { return __builtin_amdgcn_rcpf(1.0f + __builtin_amdgcn_exp2f(-g * LOG2E)); }
; template <class TEpi, bool SWI> __device__ __forceinline__ void gemm_tail2(LAS unsigned char* lds, const bf16_t* A_, const bf16_t* Bt_, int K_, int nitems_, const TEpi& E) {
;     ...
;             const int a = w >> 2, g = w & 3; f32x4 v = {0.f, 0.f, 0.f, 0.f};
; #pragma unroll
;             for (int ww = 0; ww < 8; ++ww)
; #pragma unroll
;                 for (int j = 0; j < 4; ++j) v[j] += Pp[((ww * 2 + a) * 16 + 4 * g + j) * 64 + lane];
;             E(row0 + r32, cbk * 64 + a * 32 + 8 * g + 4 * hi, v, v);
;     __device__ __forceinline__ void operator()(int row, int col, f32x4 v, f32x4) const { const float rs = rstd_of(ss, row);
;         float a[4];
; #pragma unroll
;         for (int j = 0; j < 4; ++j) { const float x = v[j] * rs; a[j] = ACT ? sigm_f(x) : x; }
;         u32x2 wv; wv.x = cvtpk(a[0], a[1]); wv.y = cvtpk(a[2], a[3]); *(u32x2*)(O + (size_t)row * ldc + col) = wv; }
.LBB0_1450:
	v_add_u32_e32 v2, s27, v155
	s_nop 1
	ds_write2st64_b32 v2, v32, v33 offset1:1
	ds_write2st64_b32 v2, v16, v17 offset0:16 offset1:17
	ds_write2st64_b32 v2, v34, v35 offset0:2 offset1:3
	ds_write2st64_b32 v2, v18, v19 offset0:18 offset1:19
	ds_write2st64_b32 v2, v36, v37 offset0:4 offset1:5
	ds_write2st64_b32 v2, v20, v21 offset0:20 offset1:21
	ds_write2st64_b32 v2, v38, v39 offset0:6 offset1:7
	ds_write2st64_b32 v2, v22, v23 offset0:22 offset1:23
	ds_write2st64_b32 v2, v40, v41 offset0:8 offset1:9
	ds_write2st64_b32 v2, v24, v25 offset0:24 offset1:25
	ds_write2st64_b32 v2, v42, v43 offset0:10 offset1:11
	ds_write2st64_b32 v2, v26, v27 offset0:26 offset1:27
	ds_write2st64_b32 v2, v44, v45 offset0:12 offset1:13
	ds_write2st64_b32 v2, v28, v29 offset0:28 offset1:29
	ds_write2st64_b32 v2, v46, v47 offset0:14 offset1:15
	ds_write2st64_b32 v2, v30, v31 offset0:30 offset1:31
	s_waitcnt lgkmcnt(0)
	s_barrier
	ds_read2st64_b32 v[2:3], v159 offset1:1
	s_lshl_b32 s0, s34, 5
	s_and_b32 s0, s0, 0xe0
	v_or_b32_e32 v0, s0, v157
	v_lshlrev_b32_e32 v11, 6, v0
	s_waitcnt lgkmcnt(0)
	v_add_f32_e32 v4, 0, v2
	v_add_f32_e32 v5, 0, v3
	ds_read2st64_b32 v[2:3], v159 offset0:2 offset1:3
	s_lshl_b32 s0, s34, 3
	s_andn2_b32 s0, s0, 63
	s_add_i32 s34, s34, s36
	s_add_i32 s30, s30, s94
	s_waitcnt lgkmcnt(0)
	v_add_f32_e32 v6, 0, v2
	v_add_f32_e32 v7, 0, v3
	ds_read2st64_b32 v[2:3], v159 offset0:32 offset1:33
	s_waitcnt lgkmcnt(0)
	v_pk_add_f32 v[4:5], v[4:5], v[2:3]
	ds_read2st64_b32 v[2:3], v159 offset0:34 offset1:35
	s_waitcnt lgkmcnt(0)
	v_pk_add_f32 v[6:7], v[6:7], v[2:3]
	ds_read2st64_b32 v[2:3], v159 offset0:64 offset1:65
	s_waitcnt lgkmcnt(0)
	v_pk_add_f32 v[4:5], v[4:5], v[2:3]
	ds_read2st64_b32 v[2:3], v159 offset0:66 offset1:67
	s_waitcnt lgkmcnt(0)
	v_pk_add_f32 v[6:7], v[6:7], v[2:3]
	ds_read2st64_b32 v[2:3], v159 offset0:96 offset1:97
	s_waitcnt lgkmcnt(0)
	v_pk_add_f32 v[4:5], v[4:5], v[2:3]
	ds_read2st64_b32 v[2:3], v159 offset0:98 offset1:99
	s_waitcnt lgkmcnt(0)
	v_pk_add_f32 v[6:7], v[6:7], v[2:3]
	ds_read2st64_b32 v[2:3], v159 offset0:128 offset1:129
	s_waitcnt lgkmcnt(0)
	v_pk_add_f32 v[4:5], v[4:5], v[2:3]
	ds_read2st64_b32 v[2:3], v159 offset0:130 offset1:131
	s_waitcnt lgkmcnt(0)
	v_pk_add_f32 v[6:7], v[6:7], v[2:3]
	ds_read2st64_b32 v[2:3], v159 offset0:160 offset1:161
	s_waitcnt lgkmcnt(0)
	v_pk_add_f32 v[4:5], v[4:5], v[2:3]
	ds_read2st64_b32 v[2:3], v159 offset0:162 offset1:163
	s_waitcnt lgkmcnt(0)
	v_pk_add_f32 v[6:7], v[6:7], v[2:3]
	ds_read2st64_b32 v[2:3], v159 offset0:192 offset1:193
	s_waitcnt lgkmcnt(0)
	v_pk_add_f32 v[4:5], v[4:5], v[2:3]
	ds_read2st64_b32 v[2:3], v159 offset0:194 offset1:195
	s_waitcnt lgkmcnt(0)
	v_pk_add_f32 v[6:7], v[6:7], v[2:3]
	ds_read2st64_b32 v[2:3], v159 offset0:224 offset1:225
	s_waitcnt lgkmcnt(0)
	v_add_f32_e32 v10, v4, v2
	v_add_f32_e32 v9, v5, v3
	ds_read2st64_b32 v[2:3], v159 offset0:226 offset1:227
	s_waitcnt lgkmcnt(0)
	v_add_f32_e32 v8, v6, v2
	v_add_f32_e32 v7, v7, v3
	global_load_dwordx4 v[2:5], v11, s[22:23] offset:48
	global_load_dwordx4 v[12:15], v11, s[22:23] offset:32
	global_load_dwordx4 v[16:19], v11, s[22:23] offset:16
	global_load_dwordx4 v[20:23], v11, s[22:23]
	v_add_u32_e32 v6, s0, v156
	s_waitcnt vmcnt(0)
	v_add_f32_e32 v12, v12, v13
	v_add_f32_e32 v14, v14, v15
	v_mov_b32_e32 v24, v21
	v_mov_b32_e32 v25, v22
	v_mov_b32_e32 v21, v23
	v_mov_b32_e32 v22, v17
	v_mov_b32_e32 v23, v18
	v_mov_b32_e32 v17, v19
	v_pk_add_f32 v[20:21], v[24:25], v[20:21]
	v_pk_add_f32 v[16:17], v[22:23], v[16:17]
	v_pk_add_f32 v[20:21], v[20:21], v[20:21] op_sel:[0,1] op_sel_hi:[1,0]
	v_pk_add_f32 v[16:17], v[16:17], v[16:17] op_sel:[0,1] op_sel_hi:[1,0]
	v_mov_b32_e32 v21, v2
	v_mov_b32_e32 v17, v3
	v_mov_b32_e32 v13, v4
	v_mov_b32_e32 v15, v5
	v_pk_add_f32 v[2:3], v[20:21], v[16:17]
	v_pk_add_f32 v[4:5], v[12:13], v[14:15]
	s_nop 0
	v_pk_add_f32 v[2:3], v[2:3], v[4:5]
	s_nop 0
	v_add_f32_e32 v2, v2, v3
	v_fmamk_f32 v2, v2, 0x3a800000, v236
	v_cmp_gt_f32_e32 vcc, s50, v2
	v_mul_f32_e32 v3, 0x4b800000, v2
	s_nop 0
	v_cndmask_b32_e32 v2, v2, v3, vcc
	v_rsq_f32_e32 v2, v2
	s_nop 0
	v_mul_f32_e32 v3, 0x45800000, v2
	v_cndmask_b32_e32 v2, v2, v3, vcc
	v_mul_f32_e32 v3, v10, v2
	v_pk_mul_f32 v[4:5], v[8:9], v[2:3] op_sel:[1,0] op_sel_hi:[0,0]
	v_mul_f32_e32 v2, v7, v2
	v_mul_f32_e32 v3, 0xbfb8aa3b, v3
	v_mul_f32_e32 v4, 0xbfb8aa3b, v4
	v_mul_f32_e32 v5, 0xbfb8aa3b, v5
	v_mul_f32_e32 v2, 0xbfb8aa3b, v2
	v_exp_f32_e32 v3, v3
	v_exp_f32_e32 v4, v4
	v_exp_f32_e32 v5, v5
	v_exp_f32_e32 v2, v2
	v_add_f32_e32 v3, 1.0, v3
	v_pk_add_f32 v[4:5], v[210:211], v[4:5] op_sel_hi:[0,1]
	v_add_f32_e32 v2, 1.0, v2
	v_rcp_f32_e32 v3, v3
	v_rcp_f32_e32 v4, v4
	v_rcp_f32_e32 v5, v5
	v_rcp_f32_e32 v7, v2
	v_cvt_pk_bf16_f32 v2, v3, v4
	v_cvt_pk_bf16_f32 v3, v5, v7
	v_mov_b64_e32 v[4:5], s[70:71]
	v_mad_u64_u32 v[4:5], s[0:1], v0, s5, v[4:5]
	v_readlane_b32 s0, v255, 14
	v_ashrrev_i32_e32 v7, 31, v6
	s_add_i32 s31, s31, s0
	v_lshl_add_u64 v[4:5], v[6:7], 1, v[4:5]
	s_cmp_ge_i32 s34, s12
	global_store_dwordx2 v[4:5], v[2:3], off
	s_barrier
	s_cbranch_scc1 .LBB0_1486

;     __device__ __forceinline__ void operator()(const AccT& acc, const Unit& u, int wr, int wc, int fr, int fq) const {
;         const int row0 = u.pm * 256 + wr * 64 + fr, col0 = u.pn * 128 + wc * 32 + 8 * fq;
;         float rsv[2][4];
;         { f32x4 pv[2][4];
; #pragma unroll
;           for (int ai = 0; ai < 2; ++ai)
; #pragma unroll
;               for (int m = 0; m < 4; ++m) pv[ai][m] = *(const f32x4*)(ss + (size_t)(row0 + ai * 128 + m * 16) * 16 + fq * 4);
; #pragma unroll
;           for (int ai = 0; ai < 2; ++ai)
; #pragma unroll
;               for (int m = 0; m < 4; ++m) { const f32x4 a = pv[ai][m]; float t = (a[0] + a[1]) + (a[2] + a[3]); t = xsum_16_32(t); rsv[ai][m] = rsqrtf(t * (1.0f / DM) + EPS); } }
.LBB0_1911:
	v_mov_b32_e32 v210, 1.0
	v_lshl_add_u32 v180, s90, 8, v184
	v_ashrrev_i32_e32 v181, 31, v180
	v_lshlrev_b64 v[130:131], 6, v[180:181]
	v_or_b32_e32 v178, 16, v180
	v_lshl_add_u64 v[130:131], v[160:161], 0, v[130:131]
	v_ashrrev_i32_e32 v179, 31, v178
	global_load_dwordx4 v[188:191], v[130:131], off
	v_lshlrev_b64 v[130:131], 6, v[178:179]
	v_lshl_add_u64 v[130:131], v[160:161], 0, v[130:131]
	global_load_dwordx4 v[206:209], v[130:131], off
	v_or_b32_e32 v176, 32, v180
	v_ashrrev_i32_e32 v177, 31, v176
	v_lshlrev_b64 v[130:131], 6, v[176:177]
	v_or_b32_e32 v174, 48, v180
	v_lshl_add_u64 v[130:131], v[160:161], 0, v[130:131]
	v_ashrrev_i32_e32 v175, 31, v174
	global_load_dwordx4 v[150:153], v[130:131], off
	v_lshlrev_b64 v[130:131], 6, v[174:175]
	v_lshl_add_u64 v[130:131], v[160:161], 0, v[130:131]
	global_load_dwordx4 v[146:149], v[130:131], off
	v_add_u32_e32 v172, 0x80, v180
	v_ashrrev_i32_e32 v173, 31, v172
	v_lshlrev_b64 v[130:131], 6, v[172:173]
	v_add_u32_e32 v170, 0x90, v180
	v_lshl_add_u64 v[130:131], v[160:161], 0, v[130:131]
	v_ashrrev_i32_e32 v171, 31, v170
	global_load_dwordx4 v[142:145], v[130:131], off
	v_lshlrev_b64 v[130:131], 6, v[170:171]
	v_lshl_add_u64 v[130:131], v[160:161], 0, v[130:131]
	global_load_dwordx4 v[138:141], v[130:131], off
	v_add_u32_e32 v168, 0xa0, v180
	v_ashrrev_i32_e32 v169, 31, v168
	v_lshlrev_b64 v[130:131], 6, v[168:169]
	v_add_u32_e32 v166, 0xb0, v180
	v_lshl_add_u64 v[130:131], v[160:161], 0, v[130:131]
	v_ashrrev_i32_e32 v167, 31, v166
	global_load_dwordx4 v[134:137], v[130:131], off
	v_lshlrev_b64 v[130:131], 6, v[166:167]
	v_lshl_add_u64 v[130:131], v[160:161], 0, v[130:131]
	global_load_dwordx4 v[130:133], v[130:131], off
	s_mov_b32 s0, 0x358637bd
	v_pk_mul_f32 v[120:121], v[120:121], v[116:117]
	v_pk_mul_f32 v[128:129], v[128:129], v[124:125]
	v_pk_mul_f32 v[112:113], v[112:113], v[108:109]
	v_pk_mul_f32 v[104:105], v[104:105], v[100:101]
	v_pk_mul_f32 v[96:97], v[96:97], v[92:93]
	v_pk_mul_f32 v[88:89], v[88:89], v[84:85]
	v_pk_mul_f32 v[80:81], v[80:81], v[76:77]
	v_pk_mul_f32 v[72:73], v[72:73], v[68:69]
	v_pk_mul_f32 v[64:65], v[64:65], v[60:61]
	v_pk_mul_f32 v[56:57], v[56:57], v[52:53]
	v_pk_mul_f32 v[48:49], v[48:49], v[44:45]
	v_pk_mul_f32 v[40:41], v[40:41], v[36:37]
	v_pk_mul_f32 v[32:33], v[32:33], v[28:29]
	v_pk_mul_f32 v[24:25], v[24:25], v[20:21]
	v_pk_mul_f32 v[16:17], v[16:17], v[12:13]
	v_pk_mul_f32 v[8:9], v[8:9], v[4:5]
	s_waitcnt vmcnt(0)
	v_mov_b32_e32 v182, v189
	v_mov_b32_e32 v183, v190
	v_mov_b32_e32 v189, v191
	v_pk_add_f32 v[182:183], v[182:183], v[188:189]
	v_mov_b32_e32 v190, v207
	v_pk_add_f32 v[182:183], v[182:183], v[182:183] op_sel:[0,1] op_sel_hi:[1,0]
	v_mov_b32_e32 v191, v208
	v_mov_b32_e32 v207, v209
	v_mov_b32_e32 v167, v182
	v_pk_add_f32 v[190:191], v[190:191], v[206:207]
	s_nop 0
	v_permlane16_swap_b32_e32 v182, v167
	v_pk_add_f32 v[190:191], v[190:191], v[190:191] op_sel:[0,1] op_sel_hi:[1,0]
	v_add_f32_e32 v183, v182, v167
	v_mov_b32_e32 v167, v190
	s_nop 1
	v_permlane16_swap_b32_e32 v190, v167
	v_add_f32_e32 v182, v190, v167
	v_mov_b32_e32 v189, v183
	v_mov_b32_e32 v188, v182
	s_nop 0
	v_permlane32_swap_b32_e32 v183, v189
	v_permlane32_swap_b32_e32 v182, v188
	v_pk_add_f32 v[188:189], v[182:183], v[188:189]
	v_mov_b64_e32 v[182:183], s[0:1]
	v_pk_fma_f32 v[188:189], v[188:189], s[4:5], v[182:183] op_sel_hi:[1,0,0]
	s_nop 0
	v_mul_f32_e32 v167, 0x4b800000, v189
	v_cmp_gt_f32_e64 s[44:45], s50, v189
	v_cmp_gt_f32_e32 vcc, s50, v188
	s_nop 0
	v_cndmask_b32_e64 v167, v189, v167, s[44:45]
	v_rsq_f32_e32 v167, v167
	v_mov_b32_e32 v189, v152
	v_mul_f32_e32 v169, 0x45800000, v167
	v_cndmask_b32_e64 v169, v167, v169, s[44:45]
	v_mul_f32_e32 v167, 0x4b800000, v188
	v_cndmask_b32_e32 v167, v188, v167, vcc
	v_mov_b32_e32 v188, v151
	v_mov_b32_e32 v151, v153
	v_pk_add_f32 v[150:151], v[188:189], v[150:151]
	v_mov_b32_e32 v188, v147
	v_mov_b32_e32 v189, v148
	v_mov_b32_e32 v147, v149
	v_pk_add_f32 v[146:147], v[188:189], v[146:147]
	v_pk_add_f32 v[150:151], v[150:151], v[150:151] op_sel:[0,1] op_sel_hi:[1,0]
	v_pk_add_f32 v[146:147], v[146:147], v[146:147] op_sel:[0,1] op_sel_hi:[1,0]
	v_mov_b32_e32 v151, v150
	v_mov_b32_e32 v147, v146
	s_nop 0
	v_permlane16_swap_b32_e32 v150, v151
	v_permlane16_swap_b32_e32 v146, v147
	v_add_f32_e32 v151, v150, v151
	v_add_f32_e32 v150, v146, v147
	v_mov_b32_e32 v153, v151
	v_mov_b32_e32 v152, v150
	s_nop 0
	v_permlane32_swap_b32_e32 v151, v153
	v_permlane32_swap_b32_e32 v150, v152
	v_pk_add_f32 v[146:147], v[150:151], v[152:153]
	v_rsq_f32_e32 v167, v167
	v_pk_fma_f32 v[146:147], v[146:147], s[4:5], v[182:183] op_sel_hi:[1,0,0]
	v_mov_b32_e32 v149, v144
	v_mul_f32_e32 v148, 0x4b800000, v147
	v_cmp_gt_f32_e64 s[44:45], s50, v147
	v_mul_f32_e32 v171, 0x45800000, v167
	v_cndmask_b32_e32 v167, v167, v171, vcc
	v_cndmask_b32_e64 v147, v147, v148, s[44:45]
	v_rsq_f32_e32 v147, v147
	v_cmp_gt_f32_e32 vcc, s50, v146
	v_mul_f32_e32 v148, 0x45800000, v147
	v_cndmask_b32_e64 v147, v147, v148, s[44:45]
	v_mul_f32_e32 v148, 0x4b800000, v146
	v_cndmask_b32_e32 v146, v146, v148, vcc
	v_rsq_f32_e32 v146, v146
	s_nop 0
	v_mul_f32_e32 v148, 0x45800000, v146
	v_cndmask_b32_e32 v146, v146, v148, vcc
	v_mov_b32_e32 v148, v143
	v_mov_b32_e32 v143, v145
	v_pk_add_f32 v[142:143], v[148:149], v[142:143]
	v_mov_b32_e32 v148, v139
	v_mov_b32_e32 v149, v140
	v_mov_b32_e32 v139, v141
	v_pk_add_f32 v[138:139], v[148:149], v[138:139]
	v_pk_add_f32 v[142:143], v[142:143], v[142:143] op_sel:[0,1] op_sel_hi:[1,0]
	v_pk_add_f32 v[138:139], v[138:139], v[138:139] op_sel:[0,1] op_sel_hi:[1,0]
	v_mov_b32_e32 v143, v142
	v_mov_b32_e32 v139, v138
; __device__ __forceinline__ unsigned cvtpk(float lo, float hi) { f32x2_t v = {lo, hi}; bf16x2_t b = __builtin_convertvector(v, bf16x2_t); return __builtin_bit_cast(unsigned, b); }
;     __device__ __forceinline__ void operator()(const AccT& acc, const Unit& u, int wr, int wc, int fr, int fq) const {
;     ...
;             for (int m = 0; m < 4; ++m) { const int row = row0 + ai * 128 + m * 16; const float rs = rsv[ai][m]; const float c1 = -rs * LOG2E, c2 = rs * rs;
;                 float a[8];
; #pragma unroll
;                 for (int n = 0; n < 2; ++n)
; #pragma unroll
;                     for (int j = 0; j < 4; ++j) { const float g_ = acc[ai][0][m][n][j]; a[n * 4 + j] = (g_ * acc[ai][1][m][n][j]) * (c2 * __builtin_amdgcn_rcpf(1.0f + __builtin_amdgcn_exp2f(g_ * c1))); }
;                 u32x4 w; w.x = cvtpk(a[0], a[1]); w.y = cvtpk(a[2], a[3]); w.z = cvtpk(a[4], a[5]); w.w = cvtpk(a[6], a[7]);
;                 *(u32x4*)(O + (size_t)row * DFF + col0) = w; }
	s_nop 0
	v_permlane16_swap_b32_e32 v142, v143
	v_permlane16_swap_b32_e32 v138, v139
	v_add_f32_e32 v143, v142, v143
	v_add_f32_e32 v142, v138, v139
	v_mov_b32_e32 v145, v143
	v_mov_b32_e32 v144, v142
	s_nop 0
	v_permlane32_swap_b32_e32 v143, v145
	v_permlane32_swap_b32_e32 v142, v144
	v_pk_add_f32 v[138:139], v[142:143], v[144:145]
	v_mov_b32_e32 v141, v136
	v_pk_fma_f32 v[138:139], v[138:139], s[4:5], v[182:183] op_sel_hi:[1,0,0]
	s_nop 0
	v_mul_f32_e32 v140, 0x4b800000, v139
	v_cmp_gt_f32_e64 s[44:45], s50, v139
	v_cmp_gt_f32_e32 vcc, s50, v138
	s_nop 0
	v_cndmask_b32_e64 v139, v139, v140, s[44:45]
	v_rsq_f32_e32 v139, v139
	s_nop 0
	v_mul_f32_e32 v140, 0x45800000, v139
	v_cndmask_b32_e64 v139, v139, v140, s[44:45]
	v_mul_f32_e32 v140, 0x4b800000, v138
	v_cndmask_b32_e32 v138, v138, v140, vcc
	v_rsq_f32_e32 v138, v138
	s_nop 0
	v_mul_f32_e32 v140, 0x45800000, v138
	v_cndmask_b32_e32 v138, v138, v140, vcc
	v_mov_b32_e32 v140, v135
	v_mov_b32_e32 v135, v137
	v_pk_add_f32 v[134:135], v[140:141], v[134:135]
	v_mov_b32_e32 v140, v131
	v_mov_b32_e32 v141, v132
	v_mov_b32_e32 v131, v133
	v_pk_add_f32 v[130:131], v[140:141], v[130:131]
	v_pk_add_f32 v[134:135], v[134:135], v[134:135] op_sel:[0,1] op_sel_hi:[1,0]
	v_pk_add_f32 v[130:131], v[130:131], v[130:131] op_sel:[0,1] op_sel_hi:[1,0]
	v_mov_b32_e32 v135, v134
	v_mov_b32_e32 v131, v130
	s_nop 0
	v_permlane16_swap_b32_e32 v134, v135
	v_permlane16_swap_b32_e32 v130, v131
	v_add_f32_e32 v135, v134, v135
	v_add_f32_e32 v134, v130, v131
	v_mov_b32_e32 v137, v135
	v_mov_b32_e32 v136, v134
	s_nop 0
	v_permlane32_swap_b32_e32 v135, v137
	v_permlane32_swap_b32_e32 v134, v136
	v_pk_add_f32 v[130:131], v[134:135], v[136:137]
	v_mul_f32_e32 v135, 0xbfb8aa3b, v169
	v_pk_mul_f32 v[136:137], v[122:123], v[134:135] op_sel:[0,1]
	s_nop 0
	v_exp_f32_e32 v136, v136
	v_exp_f32_e32 v137, v137
	v_pk_fma_f32 v[130:131], v[130:131], s[4:5], v[182:183] op_sel_hi:[1,0,0]
	v_mul_f32_e32 v134, v169, v169
	v_pk_add_f32 v[136:137], v[210:211], v[136:137] op_sel_hi:[0,1]
	s_nop 0
	v_rcp_f32_e32 v136, v136
	v_rcp_f32_e32 v137, v137
	v_mul_f32_e32 v132, 0x4b800000, v131
	v_cmp_gt_f32_e64 s[44:45], s50, v131
	v_pk_mul_f32 v[122:123], v[126:127], v[122:123]
	v_pk_mul_f32 v[126:127], v[134:135], v[136:137] op_sel_hi:[0,1]
	v_cndmask_b32_e64 v131, v131, v132, s[44:45]
	v_rsq_f32_e32 v131, v131
	v_pk_mul_f32 v[122:123], v[122:123], v[126:127]
	v_pk_mul_f32 v[126:127], v[114:115], v[134:135] op_sel:[0,1]
	s_nop 0
	v_exp_f32_e32 v126, v126
	v_exp_f32_e32 v127, v127
	v_pk_mul_f32 v[116:117], v[116:117], v[134:135] op_sel:[0,1]
	v_pk_mul_f32 v[124:125], v[124:125], v[134:135] op_sel:[0,1]
	v_exp_f32_e32 v116, v116
	v_exp_f32_e32 v117, v117
	v_mul_f32_e32 v132, 0x45800000, v131
	v_exp_f32_e32 v124, v124
	v_exp_f32_e32 v125, v125
	v_cmp_gt_f32_e32 vcc, s50, v130
	v_cndmask_b32_e64 v131, v131, v132, s[44:45]
	v_mul_f32_e32 v132, 0x4b800000, v130
	v_cndmask_b32_e32 v130, v130, v132, vcc
	v_pk_add_f32 v[126:127], v[210:211], v[126:127] op_sel_hi:[0,1]
	v_rsq_f32_e32 v130, v130
	v_rcp_f32_e32 v126, v126
	v_rcp_f32_e32 v127, v127
	v_pk_add_f32 v[116:117], v[210:211], v[116:117] op_sel_hi:[0,1]
	v_pk_add_f32 v[124:125], v[210:211], v[124:125] op_sel_hi:[0,1]
	v_rcp_f32_e32 v116, v116
	v_rcp_f32_e32 v117, v117
	v_rcp_f32_e32 v124, v124
	v_rcp_f32_e32 v125, v125
	v_mul_f32_e32 v132, 0x45800000, v130
	v_pk_mul_f32 v[114:115], v[118:119], v[114:115]
	v_pk_mul_f32 v[118:119], v[134:135], v[126:127] op_sel_hi:[0,1]
	v_cndmask_b32_e32 v130, v130, v132, vcc
	v_lshl_or_b32 v132, s14, 7, v186
	v_pk_mul_f32 v[114:115], v[114:115], v[118:119]
	v_pk_mul_f32 v[116:117], v[134:135], v[116:117] op_sel_hi:[0,1]
	v_ashrrev_i32_e32 v133, 31, v132
	v_pk_mul_f32 v[124:125], v[134:135], v[124:125] op_sel_hi:[0,1]
	v_pk_mul_f32 v[116:117], v[120:121], v[116:117]
	v_cvt_pk_bf16_f32 v120, v114, v115
	v_mov_b64_e32 v[114:115], s[70:71]
	v_pk_mul_f32 v[124:125], v[128:129], v[124:125]
	v_cvt_pk_bf16_f32 v118, v122, v123
	v_cvt_pk_bf16_f32 v121, v116, v117
	v_mad_i64_i32 v[122:123], s[0:1], v180, s97, v[114:115]
	v_lshlrev_b64 v[116:117], 1, v[132:133]
	v_cvt_pk_bf16_f32 v119, v124, v125
	v_lshl_add_u64 v[122:123], v[122:123], 0, v[116:117]
	global_store_dwordx4 v[122:123], v[118:121], off
	s_and_b64 vcc, exec, s[42:43]
	s_nop 0
	v_mul_f32_e32 v119, 0xbfb8aa3b, v167
	v_pk_mul_f32 v[120:121], v[106:107], v[118:119] op_sel:[0,1]
	s_nop 0
	v_exp_f32_e32 v120, v120
	v_exp_f32_e32 v121, v121
	v_mul_f32_e32 v118, v167, v167
	v_pk_mul_f32 v[106:107], v[110:111], v[106:107]
	v_pk_add_f32 v[120:121], v[210:211], v[120:121] op_sel_hi:[0,1]
	s_nop 0
	v_rcp_f32_e32 v120, v120
	v_rcp_f32_e32 v121, v121
	v_pk_mul_f32 v[108:109], v[108:109], v[118:119] op_sel:[0,1]
	s_nop 0
	v_exp_f32_e32 v108, v108
	v_pk_mul_f32 v[110:111], v[118:119], v[120:121] op_sel_hi:[0,1]
	v_pk_mul_f32 v[106:107], v[106:107], v[110:111]
	v_pk_mul_f32 v[110:111], v[98:99], v[118:119] op_sel:[0,1]
	s_nop 0
	v_exp_f32_e32 v110, v110
	v_exp_f32_e32 v111, v111
	v_pk_mul_f32 v[98:99], v[102:103], v[98:99]
	v_exp_f32_e32 v109, v109
	v_pk_add_f32 v[110:111], v[210:211], v[110:111] op_sel_hi:[0,1]
	s_nop 0
	v_rcp_f32_e32 v110, v110
	v_rcp_f32_e32 v111, v111
	v_pk_add_f32 v[108:109], v[210:211], v[108:109] op_sel_hi:[0,1]
	s_nop 0
	v_rcp_f32_e32 v108, v108
	v_pk_mul_f32 v[102:103], v[118:119], v[110:111] op_sel_hi:[0,1]
	v_pk_mul_f32 v[102:103], v[98:99], v[102:103]
	v_pk_mul_f32 v[98:99], v[100:101], v[118:119] op_sel:[0,1]
	s_nop 0
	v_exp_f32_e32 v98, v98
	v_exp_f32_e32 v99, v99
	v_rcp_f32_e32 v109, v109
	v_cvt_pk_bf16_f32 v100, v102, v103
	v_pk_add_f32 v[98:99], v[210:211], v[98:99] op_sel_hi:[0,1]
	s_nop 0
; __device__ __forceinline__ unsigned cvtpk(float lo, float hi) { f32x2_t v = {lo, hi}; bf16x2_t b = __builtin_convertvector(v, bf16x2_t); return __builtin_bit_cast(unsigned, b); }
;     __device__ __forceinline__ void operator()(const AccT& acc, const Unit& u, int wr, int wc, int fr, int fq) const {
;     ...
;             for (int m = 0; m < 4; ++m) { const int row = row0 + ai * 128 + m * 16; const float rs = rsv[ai][m]; const float c1 = -rs * LOG2E, c2 = rs * rs;
;                 float a[8];
; #pragma unroll
;                 for (int n = 0; n < 2; ++n)
; #pragma unroll
;                     for (int j = 0; j < 4; ++j) { const float g_ = acc[ai][0][m][n][j]; a[n * 4 + j] = (g_ * acc[ai][1][m][n][j]) * (c2 * __builtin_amdgcn_rcpf(1.0f + __builtin_amdgcn_exp2f(g_ * c1))); }
;                 u32x4 w; w.x = cvtpk(a[0], a[1]); w.y = cvtpk(a[2], a[3]); w.z = cvtpk(a[4], a[5]); w.w = cvtpk(a[6], a[7]);
;                 *(u32x4*)(O + (size_t)row * DFF + col0) = w; }
	v_rcp_f32_e32 v98, v98
	v_rcp_f32_e32 v99, v99
	v_pk_mul_f32 v[108:109], v[118:119], v[108:109] op_sel_hi:[0,1]
	v_pk_mul_f32 v[108:109], v[112:113], v[108:109]
	v_mad_i64_i32 v[102:103], s[0:1], v178, s97, v[114:115]
	v_pk_mul_f32 v[98:99], v[118:119], v[98:99] op_sel_hi:[0,1]
	v_pk_mul_f32 v[104:105], v[104:105], v[98:99]
	v_cvt_pk_bf16_f32 v98, v106, v107
	v_cvt_pk_bf16_f32 v99, v108, v109
	v_cvt_pk_bf16_f32 v101, v104, v105
	v_lshl_add_u64 v[102:103], v[102:103], 0, v[116:117]
	global_store_dwordx4 v[102:103], v[98:101], off
	s_nop 1
	v_mul_f32_e32 v99, 0xbfb8aa3b, v147
	v_pk_mul_f32 v[100:101], v[90:91], v[98:99] op_sel:[0,1]
	s_nop 0
	v_exp_f32_e32 v100, v100
	v_exp_f32_e32 v101, v101
	v_mul_f32_e32 v98, v147, v147
	v_pk_mul_f32 v[90:91], v[94:95], v[90:91]
	v_pk_add_f32 v[100:101], v[210:211], v[100:101] op_sel_hi:[0,1]
	s_nop 0
	v_rcp_f32_e32 v100, v100
	v_rcp_f32_e32 v101, v101
	v_pk_mul_f32 v[92:93], v[92:93], v[98:99] op_sel:[0,1]
	s_nop 0
	v_exp_f32_e32 v92, v92
	v_pk_mul_f32 v[94:95], v[98:99], v[100:101] op_sel_hi:[0,1]
	v_pk_mul_f32 v[90:91], v[90:91], v[94:95]
	v_pk_mul_f32 v[94:95], v[82:83], v[98:99] op_sel:[0,1]
	s_nop 0
	v_exp_f32_e32 v94, v94
	v_exp_f32_e32 v95, v95
	v_pk_mul_f32 v[82:83], v[86:87], v[82:83]
	v_exp_f32_e32 v93, v93
	v_pk_add_f32 v[94:95], v[210:211], v[94:95] op_sel_hi:[0,1]
	s_nop 0
	v_rcp_f32_e32 v94, v94
	v_rcp_f32_e32 v95, v95
	v_pk_add_f32 v[92:93], v[210:211], v[92:93] op_sel_hi:[0,1]
	s_nop 0
	v_rcp_f32_e32 v92, v92
	v_pk_mul_f32 v[86:87], v[98:99], v[94:95] op_sel_hi:[0,1]
	v_pk_mul_f32 v[86:87], v[82:83], v[86:87]
	v_pk_mul_f32 v[82:83], v[84:85], v[98:99] op_sel:[0,1]
	s_nop 0
	v_exp_f32_e32 v82, v82
	v_exp_f32_e32 v83, v83
	v_rcp_f32_e32 v93, v93
	v_cvt_pk_bf16_f32 v84, v86, v87
	v_pk_add_f32 v[82:83], v[210:211], v[82:83] op_sel_hi:[0,1]
	s_nop 0
	v_rcp_f32_e32 v82, v82
	v_rcp_f32_e32 v83, v83
	v_pk_mul_f32 v[92:93], v[98:99], v[92:93] op_sel_hi:[0,1]
	v_pk_mul_f32 v[92:93], v[96:97], v[92:93]
	v_mad_i64_i32 v[86:87], s[0:1], v176, s97, v[114:115]
	v_pk_mul_f32 v[82:83], v[98:99], v[82:83] op_sel_hi:[0,1]
	v_pk_mul_f32 v[88:89], v[88:89], v[82:83]
	v_cvt_pk_bf16_f32 v82, v90, v91
	v_cvt_pk_bf16_f32 v83, v92, v93
	v_cvt_pk_bf16_f32 v85, v88, v89
	v_lshl_add_u64 v[86:87], v[86:87], 0, v[116:117]
	global_store_dwordx4 v[86:87], v[82:85], off
	s_nop 1
	v_mul_f32_e32 v83, 0xbfb8aa3b, v146
	v_pk_mul_f32 v[84:85], v[74:75], v[82:83] op_sel:[0,1]
	s_nop 0
	v_exp_f32_e32 v84, v84
	v_exp_f32_e32 v85, v85
	v_mul_f32_e32 v82, v146, v146
	v_pk_mul_f32 v[74:75], v[78:79], v[74:75]
	v_pk_add_f32 v[84:85], v[210:211], v[84:85] op_sel_hi:[0,1]
	s_nop 0
	v_rcp_f32_e32 v84, v84
	v_rcp_f32_e32 v85, v85
	v_pk_mul_f32 v[76:77], v[76:77], v[82:83] op_sel:[0,1]
	s_nop 0
	v_exp_f32_e32 v76, v76
	v_pk_mul_f32 v[78:79], v[82:83], v[84:85] op_sel_hi:[0,1]
	v_pk_mul_f32 v[74:75], v[74:75], v[78:79]
	v_pk_mul_f32 v[78:79], v[66:67], v[82:83] op_sel:[0,1]
	s_nop 0
	v_exp_f32_e32 v78, v78
	v_exp_f32_e32 v79, v79
	v_pk_mul_f32 v[66:67], v[70:71], v[66:67]
	v_exp_f32_e32 v77, v77
	v_pk_add_f32 v[78:79], v[210:211], v[78:79] op_sel_hi:[0,1]
	s_nop 0
	v_rcp_f32_e32 v78, v78
	v_rcp_f32_e32 v79, v79
	v_pk_add_f32 v[76:77], v[210:211], v[76:77] op_sel_hi:[0,1]
	s_nop 0
	v_rcp_f32_e32 v76, v76
	v_pk_mul_f32 v[70:71], v[82:83], v[78:79] op_sel_hi:[0,1]
	v_pk_mul_f32 v[70:71], v[66:67], v[70:71]
	v_pk_mul_f32 v[66:67], v[68:69], v[82:83] op_sel:[0,1]
	s_nop 0
	v_exp_f32_e32 v66, v66
	v_exp_f32_e32 v67, v67
	v_rcp_f32_e32 v77, v77
	v_cvt_pk_bf16_f32 v68, v70, v71
	v_pk_add_f32 v[66:67], v[210:211], v[66:67] op_sel_hi:[0,1]
	s_nop 0
	v_rcp_f32_e32 v66, v66
	v_rcp_f32_e32 v67, v67
	v_pk_mul_f32 v[76:77], v[82:83], v[76:77] op_sel_hi:[0,1]
	v_pk_mul_f32 v[76:77], v[80:81], v[76:77]
	v_mad_i64_i32 v[70:71], s[0:1], v174, s97, v[114:115]
	v_pk_mul_f32 v[66:67], v[82:83], v[66:67] op_sel_hi:[0,1]
	v_pk_mul_f32 v[72:73], v[72:73], v[66:67]
	v_cvt_pk_bf16_f32 v66, v74, v75
	v_cvt_pk_bf16_f32 v67, v76, v77
	v_cvt_pk_bf16_f32 v69, v72, v73
	v_lshl_add_u64 v[70:71], v[70:71], 0, v[116:117]
	global_store_dwordx4 v[70:71], v[66:69], off
	s_nop 1
	v_mul_f32_e32 v67, 0xbfb8aa3b, v139
	v_pk_mul_f32 v[68:69], v[58:59], v[66:67] op_sel:[0,1]
	s_nop 0
	v_exp_f32_e32 v68, v68
	v_exp_f32_e32 v69, v69
	v_mul_f32_e32 v66, v139, v139
	v_pk_mul_f32 v[58:59], v[62:63], v[58:59]
	v_pk_add_f32 v[68:69], v[210:211], v[68:69] op_sel_hi:[0,1]
	s_nop 0
	v_rcp_f32_e32 v68, v68
	v_rcp_f32_e32 v69, v69
	v_pk_mul_f32 v[60:61], v[60:61], v[66:67] op_sel:[0,1]
	s_nop 0
	v_exp_f32_e32 v60, v60
	v_pk_mul_f32 v[62:63], v[66:67], v[68:69] op_sel_hi:[0,1]
	v_pk_mul_f32 v[58:59], v[58:59], v[62:63]
	v_pk_mul_f32 v[62:63], v[50:51], v[66:67] op_sel:[0,1]
	s_nop 0
	v_exp_f32_e32 v62, v62
	v_exp_f32_e32 v63, v63
	v_pk_mul_f32 v[50:51], v[54:55], v[50:51]
	v_exp_f32_e32 v61, v61
	v_pk_add_f32 v[62:63], v[210:211], v[62:63] op_sel_hi:[0,1]
	s_nop 0
	v_rcp_f32_e32 v62, v62
	v_rcp_f32_e32 v63, v63
	v_pk_add_f32 v[60:61], v[210:211], v[60:61] op_sel_hi:[0,1]
	s_nop 0
	v_rcp_f32_e32 v60, v60
	v_pk_mul_f32 v[54:55], v[66:67], v[62:63] op_sel_hi:[0,1]
	v_pk_mul_f32 v[54:55], v[50:51], v[54:55]
	v_pk_mul_f32 v[50:51], v[52:53], v[66:67] op_sel:[0,1]
	s_nop 0
	v_exp_f32_e32 v50, v50
	v_exp_f32_e32 v51, v51
	v_rcp_f32_e32 v61, v61
	v_cvt_pk_bf16_f32 v52, v54, v55
	v_pk_add_f32 v[50:51], v[210:211], v[50:51] op_sel_hi:[0,1]
	s_nop 0
	v_rcp_f32_e32 v50, v50
	v_rcp_f32_e32 v51, v51
	v_pk_mul_f32 v[60:61], v[66:67], v[60:61] op_sel_hi:[0,1]
	v_pk_mul_f32 v[60:61], v[64:65], v[60:61]
	v_mad_i64_i32 v[54:55], s[0:1], v172, s97, v[114:115]
	v_pk_mul_f32 v[50:51], v[66:67], v[50:51] op_sel_hi:[0,1]
; __device__ __forceinline__ unsigned cvtpk(float lo, float hi) { f32x2_t v = {lo, hi}; bf16x2_t b = __builtin_convertvector(v, bf16x2_t); return __builtin_bit_cast(unsigned, b); }
; #define PG8_BAR __builtin_amdgcn_s_barrier()
; template <class Epi, class Sched>
; __device__ __forceinline__ void gemm_phase(LAS unsigned char* lds, const Gemm g, const Sched& S, const Epi& E) {
;     ...
;         if (!has_next) break;
; #pragma unroll
;         for (int a = 0; a < 2; ++a)
; #pragma unroll
;             for (int b = 0; b < 2; ++b)
; #pragma unroll
;                 for (int m = 0; m < 4; ++m)
; #pragma unroll
;                     for (int n = 0; n < 2; ++n) acc[a][b][m][n] = (f32x4){0.f, 0.f, 0.f, 0.f};
;         cur = nxt; cA = nA; cB = nB; ++ui;
;         if (wr == 1) PG8_BAR;
;     }
;     __device__ __forceinline__ void operator()(const AccT& acc, const Unit& u, int wr, int wc, int fr, int fq) const {
;     ...
;             for (int m = 0; m < 4; ++m) { const int row = row0 + ai * 128 + m * 16; const float rs = rsv[ai][m]; const float c1 = -rs * LOG2E, c2 = rs * rs;
;                 float a[8];
; #pragma unroll
;                 for (int n = 0; n < 2; ++n)
; #pragma unroll
;                     for (int j = 0; j < 4; ++j) { const float g_ = acc[ai][0][m][n][j]; a[n * 4 + j] = (g_ * acc[ai][1][m][n][j]) * (c2 * __builtin_amdgcn_rcpf(1.0f + __builtin_amdgcn_exp2f(g_ * c1))); }
;                 u32x4 w; w.x = cvtpk(a[0], a[1]); w.y = cvtpk(a[2], a[3]); w.z = cvtpk(a[4], a[5]); w.w = cvtpk(a[6], a[7]);
;                 *(u32x4*)(O + (size_t)row * DFF + col0) = w; }
	v_pk_mul_f32 v[56:57], v[56:57], v[50:51]
	v_cvt_pk_bf16_f32 v50, v58, v59
	v_cvt_pk_bf16_f32 v51, v60, v61
	v_cvt_pk_bf16_f32 v53, v56, v57
	v_lshl_add_u64 v[54:55], v[54:55], 0, v[116:117]
	global_store_dwordx4 v[54:55], v[50:53], off
	s_nop 1
	v_mul_f32_e32 v51, 0xbfb8aa3b, v138
	v_pk_mul_f32 v[52:53], v[42:43], v[50:51] op_sel:[0,1]
	s_nop 0
	v_exp_f32_e32 v52, v52
	v_exp_f32_e32 v53, v53
	v_mul_f32_e32 v50, v138, v138
	v_pk_mul_f32 v[42:43], v[46:47], v[42:43]
	v_pk_add_f32 v[52:53], v[210:211], v[52:53] op_sel_hi:[0,1]
	s_nop 0
	v_rcp_f32_e32 v52, v52
	v_rcp_f32_e32 v53, v53
	v_pk_mul_f32 v[44:45], v[44:45], v[50:51] op_sel:[0,1]
	s_nop 0
	v_exp_f32_e32 v44, v44
	v_pk_mul_f32 v[46:47], v[50:51], v[52:53] op_sel_hi:[0,1]
	v_pk_mul_f32 v[42:43], v[42:43], v[46:47]
	v_pk_mul_f32 v[46:47], v[34:35], v[50:51] op_sel:[0,1]
	s_nop 0
	v_exp_f32_e32 v46, v46
	v_exp_f32_e32 v47, v47
	v_pk_mul_f32 v[34:35], v[38:39], v[34:35]
	v_exp_f32_e32 v45, v45
	v_pk_add_f32 v[46:47], v[210:211], v[46:47] op_sel_hi:[0,1]
	s_nop 0
	v_rcp_f32_e32 v46, v46
	v_rcp_f32_e32 v47, v47
	v_pk_add_f32 v[44:45], v[210:211], v[44:45] op_sel_hi:[0,1]
	s_nop 0
	v_rcp_f32_e32 v44, v44
	v_pk_mul_f32 v[38:39], v[50:51], v[46:47] op_sel_hi:[0,1]
	v_pk_mul_f32 v[38:39], v[34:35], v[38:39]
	v_pk_mul_f32 v[34:35], v[36:37], v[50:51] op_sel:[0,1]
	s_nop 0
	v_exp_f32_e32 v34, v34
	v_exp_f32_e32 v35, v35
	v_rcp_f32_e32 v45, v45
	v_cvt_pk_bf16_f32 v36, v38, v39
	v_pk_add_f32 v[34:35], v[210:211], v[34:35] op_sel_hi:[0,1]
	s_nop 0
	v_rcp_f32_e32 v34, v34
	v_rcp_f32_e32 v35, v35
	v_pk_mul_f32 v[44:45], v[50:51], v[44:45] op_sel_hi:[0,1]
	v_pk_mul_f32 v[44:45], v[48:49], v[44:45]
	v_mad_i64_i32 v[38:39], s[0:1], v170, s97, v[114:115]
	v_pk_mul_f32 v[34:35], v[50:51], v[34:35] op_sel_hi:[0,1]
	v_pk_mul_f32 v[40:41], v[40:41], v[34:35]
	v_cvt_pk_bf16_f32 v34, v42, v43
	v_cvt_pk_bf16_f32 v35, v44, v45
	v_cvt_pk_bf16_f32 v37, v40, v41
	v_lshl_add_u64 v[38:39], v[38:39], 0, v[116:117]
	global_store_dwordx4 v[38:39], v[34:37], off
	s_nop 1
	v_mul_f32_e32 v35, 0xbfb8aa3b, v131
	v_pk_mul_f32 v[36:37], v[26:27], v[34:35] op_sel:[0,1]
	s_nop 0
	v_exp_f32_e32 v36, v36
	v_exp_f32_e32 v37, v37
	v_mul_f32_e32 v34, v131, v131
	v_pk_mul_f32 v[26:27], v[30:31], v[26:27]
	v_pk_add_f32 v[36:37], v[210:211], v[36:37] op_sel_hi:[0,1]
	s_nop 0
	v_rcp_f32_e32 v36, v36
	v_rcp_f32_e32 v37, v37
	v_pk_mul_f32 v[28:29], v[28:29], v[34:35] op_sel:[0,1]
	s_nop 0
	v_exp_f32_e32 v28, v28
	v_pk_mul_f32 v[30:31], v[34:35], v[36:37] op_sel_hi:[0,1]
	v_pk_mul_f32 v[26:27], v[26:27], v[30:31]
	v_pk_mul_f32 v[30:31], v[18:19], v[34:35] op_sel:[0,1]
	s_nop 0
	v_exp_f32_e32 v30, v30
	v_exp_f32_e32 v31, v31
	v_pk_mul_f32 v[18:19], v[22:23], v[18:19]
	v_exp_f32_e32 v29, v29
	v_pk_add_f32 v[30:31], v[210:211], v[30:31] op_sel_hi:[0,1]
	s_nop 0
	v_rcp_f32_e32 v30, v30
	v_rcp_f32_e32 v31, v31
	v_pk_add_f32 v[28:29], v[210:211], v[28:29] op_sel_hi:[0,1]
	s_nop 0
	v_rcp_f32_e32 v28, v28
	v_pk_mul_f32 v[22:23], v[34:35], v[30:31] op_sel_hi:[0,1]
	v_pk_mul_f32 v[22:23], v[18:19], v[22:23]
	v_pk_mul_f32 v[18:19], v[20:21], v[34:35] op_sel:[0,1]
	s_nop 0
	v_exp_f32_e32 v18, v18
	v_exp_f32_e32 v19, v19
	v_rcp_f32_e32 v29, v29
	v_cvt_pk_bf16_f32 v20, v22, v23
	v_pk_add_f32 v[18:19], v[210:211], v[18:19] op_sel_hi:[0,1]
	s_nop 0
	v_rcp_f32_e32 v18, v18
	v_rcp_f32_e32 v19, v19
	v_pk_mul_f32 v[28:29], v[34:35], v[28:29] op_sel_hi:[0,1]
	v_pk_mul_f32 v[28:29], v[32:33], v[28:29]
	v_mad_i64_i32 v[22:23], s[0:1], v168, s97, v[114:115]
	v_pk_mul_f32 v[18:19], v[34:35], v[18:19] op_sel_hi:[0,1]
	v_pk_mul_f32 v[24:25], v[24:25], v[18:19]
	v_cvt_pk_bf16_f32 v18, v26, v27
	v_cvt_pk_bf16_f32 v19, v28, v29
	v_cvt_pk_bf16_f32 v21, v24, v25
	v_lshl_add_u64 v[22:23], v[22:23], 0, v[116:117]
	global_store_dwordx4 v[22:23], v[18:21], off
	s_nop 1
	v_mul_f32_e32 v19, 0xbfb8aa3b, v130
	v_pk_mul_f32 v[20:21], v[10:11], v[18:19] op_sel:[0,1]
	s_nop 0
	v_exp_f32_e32 v20, v20
	v_exp_f32_e32 v21, v21
	v_mul_f32_e32 v18, v130, v130
	v_pk_mul_f32 v[10:11], v[14:15], v[10:11]
	v_pk_add_f32 v[20:21], v[210:211], v[20:21] op_sel_hi:[0,1]
	s_nop 0
	v_rcp_f32_e32 v20, v20
	v_rcp_f32_e32 v21, v21
	v_pk_mul_f32 v[12:13], v[12:13], v[18:19] op_sel:[0,1]
	s_nop 0
	v_exp_f32_e32 v12, v12
	v_pk_mul_f32 v[14:15], v[18:19], v[20:21] op_sel_hi:[0,1]
	v_pk_mul_f32 v[10:11], v[10:11], v[14:15]
	v_pk_mul_f32 v[14:15], v[2:3], v[18:19] op_sel:[0,1]
	s_nop 0
	v_exp_f32_e32 v14, v14
	v_exp_f32_e32 v15, v15
	v_pk_mul_f32 v[2:3], v[6:7], v[2:3]
	v_exp_f32_e32 v13, v13
	v_pk_add_f32 v[14:15], v[210:211], v[14:15] op_sel_hi:[0,1]
	s_nop 0
	v_rcp_f32_e32 v14, v14
	v_rcp_f32_e32 v15, v15
	v_pk_add_f32 v[12:13], v[210:211], v[12:13] op_sel_hi:[0,1]
	s_nop 0
	v_rcp_f32_e32 v12, v12
	v_pk_mul_f32 v[6:7], v[18:19], v[14:15] op_sel_hi:[0,1]
	v_pk_mul_f32 v[6:7], v[2:3], v[6:7]
	v_pk_mul_f32 v[2:3], v[4:5], v[18:19] op_sel:[0,1]
	s_nop 0
	v_exp_f32_e32 v2, v2
	v_exp_f32_e32 v3, v3
	v_rcp_f32_e32 v13, v13
	v_cvt_pk_bf16_f32 v4, v6, v7
	v_pk_add_f32 v[2:3], v[210:211], v[2:3] op_sel_hi:[0,1]
	s_nop 0
	v_rcp_f32_e32 v2, v2
	v_rcp_f32_e32 v3, v3
	v_pk_mul_f32 v[12:13], v[18:19], v[12:13] op_sel_hi:[0,1]
	v_pk_mul_f32 v[12:13], v[16:17], v[12:13]
	v_mad_i64_i32 v[6:7], s[0:1], v166, s97, v[114:115]
	v_pk_mul_f32 v[2:3], v[18:19], v[2:3] op_sel_hi:[0,1]
	v_pk_mul_f32 v[8:9], v[8:9], v[2:3]
	v_cvt_pk_bf16_f32 v2, v10, v11
	v_cvt_pk_bf16_f32 v3, v12, v13
	v_cvt_pk_bf16_f32 v5, v8, v9
	v_lshl_add_u64 v[6:7], v[6:7], 0, v[116:117]
	s_mov_b64 s[0:1], -1
	global_store_dwordx4 v[6:7], v[2:5], off
	s_cbranch_vccnz .LBB0_1899
	s_andn2_b64 vcc, exec, s[40:41]
	s_cbranch_vccnz .LBB0_1898
	s_barrier
	s_branch .LBB0_1898
